# t8 + norm row loops: shift/scale loads hoisted (loaded once per wave for the group-0 rows into spare VGPRs, reloaded only when the row group changes)
# speedup vs baseline: 1.0074x; 1.0074x over previous
.LBB0_461:
	s_add_i32 s5, s4, 0xffffe000
	s_ashr_i32 s5, s5, 10
	s_add_i32 s5, s5, 1
	s_cmpk_gt_i32 s4, 0x1fff
	v_lshl_add_u64 v[34:35], s[6:7], 0, v[102:103]
	s_cselect_b32 s5, s5, 0
	v_add_co_u32_e32 v34, vcc, 0x27a00000, v34
	v_mad_i64_i32 v[36:37], s[8:9], s5, v245, v[98:99]
	s_nop 0
	v_addc_co_u32_e32 v35, vcc, 0, v35, vcc
	v_add_co_u32_e32 v70, vcc, 0x2000, v36
	s_nop 1
	v_addc_co_u32_e32 v71, vcc, 0, v37, vcc
	global_load_dwordx4 v[210:213], v[36:37], off
	global_load_dwordx4 v[202:205], v[36:37], off offset:1024
	global_load_dwordx4 v[214:217], v[70:71], off
	global_load_dwordx4 v[206:209], v[70:71], off offset:1024
	global_load_dwordx2 v[114:115], v[34:35], off
	global_load_dwordx2 v[116:117], v[34:35], off offset:512
	global_load_dwordx2 v[120:121], v[34:35], off offset:1024
	global_load_dwordx2 v[104:105], v[34:35], off offset:1536
	global_load_dwordx4 v[194:197], v[36:37], off offset:2048
	global_load_dwordx4 v[186:189], v[36:37], off offset:3072
	v_add_co_u32_e32 v38, vcc, s97, v36
	s_nop 1
	v_addc_co_u32_e32 v39, vcc, 0, v37, vcc
	v_add_co_u32_e32 v40, vcc, s91, v36
	s_nop 1
	v_addc_co_u32_e32 v41, vcc, 0, v37, vcc
	global_load_dwordx4 v[178:181], v[38:39], off
	global_load_dwordx4 v[170:173], v[38:39], off offset:1024
	global_load_dwordx4 v[182:185], v[40:41], off
	global_load_dwordx4 v[174:177], v[40:41], off offset:1024
	global_load_dwordx2 v[122:123], v[34:35], off offset:2048
	global_load_dwordx2 v[146:147], v[34:35], off offset:2560
	global_load_dwordx2 v[148:149], v[34:35], off offset:3072
	global_load_dwordx2 v[108:109], v[34:35], off offset:3584
	global_load_dwordx4 v[162:165], v[38:39], off offset:2048
	s_nop 0
	global_load_dwordx4 v[154:157], v[38:39], off offset:3072
	global_load_dwordx4 v[166:169], v[40:41], off offset:2048
	s_nop 0
	global_load_dwordx4 v[158:161], v[40:41], off offset:3072
	s_nop 0
	global_load_dwordx4 v[198:201], v[70:71], off offset:2048
	s_nop 0
	global_load_dwordx4 v[190:193], v[70:71], off offset:3072
	s_waitcnt vmcnt(14)
	v_lshlrev_b32_e32 v113, 16, v104
	v_and_b32_e32 v111, 0xffff0000, v104
	v_lshlrev_b32_e32 v118, 16, v105
	v_and_b32_e32 v119, 0xffff0000, v105
	s_waitcnt vmcnt(6)
	v_lshlrev_b32_e32 v107, 16, v108
	v_and_b32_e32 v105, 0xffff0000, v108
	v_lshlrev_b32_e32 v108, 16, v109
	v_and_b32_e32 v109, 0xffff0000, v109
	v_and_b32_e32 v139, 0xffff0000, v115
	v_and_b32_e32 v137, 0xffff0000, v114
	v_lshlrev_b32_e32 v138, 16, v115
	v_mul_f32_e32 v0, v139, v139
	v_lshlrev_b32_e32 v136, 16, v114
	v_pk_fma_f32 v[114:115], v[138:139], v[138:139], v[0:1] op_sel_hi:[1,1,0]
	v_and_b32_e32 v135, 0xffff0000, v117
	v_and_b32_e32 v134, 0xffff0000, v116
	v_mul_f32_e32 v0, v137, v137
	v_lshlrev_b32_e32 v133, 16, v117
	v_lshlrev_b32_e32 v132, 16, v116
	v_pk_mul_f32 v[116:117], v[134:135], v[134:135]
	v_lshlrev_b32_e32 v128, 16, v120
	v_and_b32_e32 v129, 0xffff0000, v120
	v_lshlrev_b32_e32 v130, 16, v121
	v_and_b32_e32 v131, 0xffff0000, v121
	v_pk_fma_f32 v[120:121], v[136:137], v[136:137], v[0:1] op_sel_hi:[1,1,0]
	v_pk_fma_f32 v[116:117], v[132:133], v[132:133], v[116:117]
	v_mov_b32_e32 v112, v120
	v_mov_b32_e32 v124, v114
	v_mov_b32_e32 v125, v113
	v_mul_f32_e32 v104, v111, v111
	v_pk_add_f32 v[114:115], v[120:121], v[114:115]
	v_pk_mul_f32 v[120:121], v[112:113], v[124:125]
	v_pk_add_f32 v[116:117], v[116:117], v[116:117] op_sel:[0,1] op_sel_hi:[1,0]
	v_mov_b32_e32 v115, v121
	v_mov_b32_e32 v117, v104
	v_mul_f32_e32 v0, v129, v129
	v_pk_add_f32 v[114:115], v[114:115], v[116:117]
	v_pk_fma_f32 v[116:117], v[128:129], v[128:129], v[0:1] op_sel_hi:[1,1,0]
	v_mul_f32_e32 v0, v131, v131
	v_mul_f32_e32 v106, v118, v118
	v_mul_f32_e32 v110, v119, v119
	v_pk_fma_f32 v[120:121], v[130:131], v[130:131], v[0:1] op_sel_hi:[1,1,0]
	v_mov_b32_e32 v117, v106
	v_mov_b32_e32 v121, v110
	v_pk_add_f32 v[116:117], v[116:117], v[120:121]
	v_and_b32_e32 v127, 0xffff0000, v123
	v_and_b32_e32 v126, 0xffff0000, v122
	v_pk_add_f32 v[150:151], v[114:115], v[116:117]
	v_lshlrev_b32_e32 v125, 16, v123
	v_lshlrev_b32_e32 v124, 16, v122
	v_pk_mul_f32 v[114:115], v[126:127], v[126:127]
	v_and_b32_e32 v123, 0xffff0000, v147
	v_pk_fma_f32 v[114:115], v[124:125], v[124:125], v[114:115]
	v_and_b32_e32 v122, 0xffff0000, v146
	v_pk_add_f32 v[152:153], v[114:115], v[114:115] op_sel:[0,1] op_sel_hi:[1,0]
	v_lshlrev_b32_e32 v121, 16, v147
	v_lshlrev_b32_e32 v120, 16, v146
	v_pk_mul_f32 v[114:115], v[122:123], v[122:123]
	v_lshlrev_b32_e32 v116, 16, v149
	v_pk_fma_f32 v[146:147], v[120:121], v[120:121], v[114:115]
	v_lshlrev_b32_e32 v114, 16, v148
	v_and_b32_e32 v115, 0xffff0000, v148
	v_and_b32_e32 v117, 0xffff0000, v149
	v_pk_add_f32 v[148:149], v[150:151], v[150:151] op_sel:[0,1] op_sel_hi:[1,0]
	v_mov_b32_e32 v150, v152
	v_mov_b32_e32 v106, v148
	v_mov_b32_e32 v151, v107
	v_mul_f32_e32 v0, v105, v105
	v_pk_add_f32 v[148:149], v[148:149], v[152:153]
	v_pk_mul_f32 v[150:151], v[106:107], v[150:151]
	v_pk_add_f32 v[146:147], v[146:147], v[146:147] op_sel:[0,1] op_sel_hi:[1,0]
	v_mov_b32_e32 v149, v151
	v_mov_b32_e32 v147, v0
	v_mul_f32_e32 v0, v115, v115
	v_pk_add_f32 v[146:147], v[148:149], v[146:147]
	v_pk_fma_f32 v[148:149], v[114:115], v[114:115], v[0:1] op_sel_hi:[1,1,0]
	v_mul_f32_e32 v0, v117, v117
	v_mul_f32_e32 v104, v108, v108
	v_mul_f32_e32 v110, v109, v109
	v_pk_fma_f32 v[150:151], v[116:117], v[116:117], v[0:1] op_sel_hi:[1,1,0]
	v_mov_b32_e32 v149, v104
	v_mov_b32_e32 v151, v110
	v_pk_add_f32 v[148:149], v[148:149], v[150:151]
	v_pk_add_f32 v[94:95], v[214:215], 1.0 op_sel_hi:[1,0]
	v_pk_add_f32 v[146:147], v[146:147], v[148:149]
	v_pk_add_f32 v[96:97], v[216:217], 1.0 op_sel_hi:[1,0]
	v_add_f32_e32 v0, v146, v147
	v_lshl_add_u64 v[146:147], s[6:7], 0, v[100:101]
	v_pk_add_f32 v[88:89], v[208:209], 1.0 op_sel_hi:[1,0]
	v_pk_add_f32 v[86:87], v[206:207], 1.0 op_sel_hi:[1,0]
	s_waitcnt vmcnt(1)
	v_pk_add_f32 v[80:81], v[200:201], 1.0 op_sel_hi:[1,0]
	s_nop 1
	v_add_f32_dpp v0, v0, v0 quad_perm:[1,0,3,2] row_mask:0xf bank_mask:0xf
	v_pk_add_f32 v[78:79], v[198:199], 1.0 op_sel_hi:[1,0]
	v_mov_b32_e32 v110, v113
	s_waitcnt vmcnt(0)
	v_pk_add_f32 v[72:73], v[192:193], 1.0 op_sel_hi:[1,0]
	v_pk_add_f32 v[70:71], v[190:191], 1.0 op_sel_hi:[1,0]
	s_nop 1
	v_add_f32_dpp v0, v0, v0 quad_perm:[2,3,0,1] row_mask:0xf bank_mask:0xf
	v_pk_add_f32 v[64:65], v[184:185], 1.0 op_sel_hi:[1,0]
	v_pk_add_f32 v[62:63], v[182:183], 1.0 op_sel_hi:[1,0]
	v_pk_add_f32 v[56:57], v[176:177], 1.0 op_sel_hi:[1,0]
	v_pk_add_f32 v[54:55], v[174:175], 1.0 op_sel_hi:[1,0]
	s_nop 1
	v_add_f32_dpp v0, v0, v0 row_half_mirror row_mask:0xf bank_mask:0xf
	v_pk_add_f32 v[48:49], v[168:169], 1.0 op_sel_hi:[1,0]
	v_pk_add_f32 v[46:47], v[166:167], 1.0 op_sel_hi:[1,0]
	v_readlane_b32 s8, v254, 13
	s_add_i32 s4, s4, s8
	s_nop 1
	v_add_f32_dpp v0, v0, v0 row_mirror row_mask:0xf bank_mask:0xf
	v_pk_add_f32 v[40:41], v[160:161], 1.0 op_sel_hi:[1,0]
	v_pk_add_f32 v[38:39], v[158:159], 1.0 op_sel_hi:[1,0]
	s_add_u32 s6, s6, s86
	s_addc_u32 s7, s7, s87
	v_mov_b32_e32 v104, v0
	s_nop 1
	v_permlane16_swap_b32 v0, v104
	v_add_f32_e32 v0, v0, v104
	s_cmpk_lt_i32 s4, 0x2800
	v_readlane_b32 s9, v254, 14
	v_mov_b32_e32 v104, v0
	s_nop 1
	v_permlane32_swap_b32 v0, v104
	v_add_f32_e32 v0, v0, v104
	v_fmamk_f32 v0, v0, 0x3a000000, v224
	v_rsq_f32_e32 v0, v0
	v_mov_b32_e32 v104, v107
	v_pk_mul_f32 v[136:137], v[0:1], v[136:137] op_sel_hi:[0,1]
	v_pk_mul_f32 v[138:139], v[0:1], v[138:139] op_sel_hi:[0,1]
	v_pk_mul_f32 v[136:137], v[2:3], v[136:137]
	v_pk_mul_f32 v[138:139], v[4:5], v[138:139]
	v_pk_fma_f32 v[90:91], v[94:95], v[136:137], v[210:211]
	v_pk_fma_f32 v[92:93], v[96:97], v[138:139], v[212:213]
	v_cvt_pk_bf16_f32 v94, v90, v91
	v_add_co_u32_e32 v90, vcc, s51, v146
	v_cvt_pk_bf16_f32 v95, v92, v93
	s_nop 0
	v_addc_co_u32_e32 v91, vcc, 0, v147, vcc
	v_mov_b32_e32 v92, v133
	v_mov_b32_e32 v93, v135
	v_mov_b32_e32 v133, v134
	global_store_dwordx2 v[90:91], v[94:95], off
	v_pk_mul_f32 v[92:93], v[0:1], v[92:93] op_sel_hi:[0,1]
	v_pk_mul_f32 v[94:95], v[0:1], v[132:133] op_sel_hi:[0,1]
	v_pk_mul_f32 v[94:95], v[6:7], v[94:95]
	v_pk_mul_f32 v[92:93], v[8:9], v[92:93]
	v_pk_fma_f32 v[82:83], v[86:87], v[94:95], v[202:203]
	v_pk_fma_f32 v[84:85], v[88:89], v[92:93], v[204:205]
	v_cvt_pk_bf16_f32 v82, v82, v83
	v_cvt_pk_bf16_f32 v83, v84, v85
	global_store_dwordx2 v[90:91], v[82:83], off offset:512
	v_pk_mul_f32 v[82:83], v[0:1], v[130:131] op_sel_hi:[0,1]
	v_pk_mul_f32 v[84:85], v[0:1], v[128:129] op_sel_hi:[0,1]
	v_pk_mul_f32 v[84:85], v[10:11], v[84:85]
	v_pk_mul_f32 v[82:83], v[12:13], v[82:83]
	v_pk_fma_f32 v[74:75], v[78:79], v[84:85], v[194:195]
	v_pk_fma_f32 v[76:77], v[80:81], v[82:83], v[196:197]
	v_cvt_pk_bf16_f32 v74, v74, v75
	v_cvt_pk_bf16_f32 v75, v76, v77
	global_store_dwordx2 v[90:91], v[74:75], off offset:1024
	v_pk_mul_f32 v[74:75], v[118:119], v[0:1] op_sel_hi:[1,0]
	v_pk_mul_f32 v[76:77], v[110:111], v[0:1] op_sel_hi:[1,0]
	v_pk_mul_f32 v[74:75], v[16:17], v[74:75]
	v_pk_mul_f32 v[76:77], v[14:15], v[76:77]
	v_pk_fma_f32 v[68:69], v[72:73], v[74:75], v[188:189]
	v_pk_fma_f32 v[66:67], v[70:71], v[76:77], v[186:187]
	s_nop 0
	v_cvt_pk_bf16_f32 v66, v66, v67
	v_cvt_pk_bf16_f32 v67, v68, v69
	global_store_dwordx2 v[90:91], v[66:67], off offset:1536
	v_mov_b32_e32 v66, v125
	v_mov_b32_e32 v67, v127
	v_mov_b32_e32 v125, v126
	v_pk_mul_f32 v[66:67], v[0:1], v[66:67] op_sel_hi:[0,1]
	v_pk_mul_f32 v[68:69], v[0:1], v[124:125] op_sel_hi:[0,1]
	v_pk_mul_f32 v[68:69], v[18:19], v[68:69]
	v_pk_mul_f32 v[66:67], v[20:21], v[66:67]
	v_pk_fma_f32 v[58:59], v[62:63], v[68:69], v[178:179]
	v_pk_fma_f32 v[60:61], v[64:65], v[66:67], v[180:181]
	v_cvt_pk_bf16_f32 v58, v58, v59
	v_cvt_pk_bf16_f32 v59, v60, v61
	global_store_dwordx2 v[90:91], v[58:59], off offset:2048
	v_mov_b32_e32 v58, v121
	v_mov_b32_e32 v59, v123
	v_mov_b32_e32 v121, v122
	v_pk_mul_f32 v[58:59], v[0:1], v[58:59] op_sel_hi:[0,1]
	v_pk_mul_f32 v[60:61], v[0:1], v[120:121] op_sel_hi:[0,1]
	v_pk_mul_f32 v[60:61], v[22:23], v[60:61]
	v_pk_mul_f32 v[58:59], v[24:25], v[58:59]
	v_pk_fma_f32 v[50:51], v[54:55], v[60:61], v[170:171]
	v_pk_fma_f32 v[52:53], v[56:57], v[58:59], v[172:173]
	v_cvt_pk_bf16_f32 v50, v50, v51
	v_cvt_pk_bf16_f32 v51, v52, v53
	global_store_dwordx2 v[90:91], v[50:51], off offset:2560
	v_pk_mul_f32 v[50:51], v[0:1], v[116:117] op_sel_hi:[0,1]
	v_pk_mul_f32 v[52:53], v[0:1], v[114:115] op_sel_hi:[0,1]
	v_pk_mul_f32 v[52:53], v[26:27], v[52:53]
	v_pk_mul_f32 v[50:51], v[28:29], v[50:51]
	v_pk_fma_f32 v[42:43], v[46:47], v[52:53], v[162:163]
	v_pk_fma_f32 v[44:45], v[48:49], v[50:51], v[164:165]
	v_cvt_pk_bf16_f32 v42, v42, v43
	v_cvt_pk_bf16_f32 v43, v44, v45
	global_store_dwordx2 v[90:91], v[42:43], off offset:3072
	v_pk_mul_f32 v[42:43], v[108:109], v[0:1] op_sel_hi:[1,0]
	v_pk_mul_f32 v[44:45], v[104:105], v[0:1] op_sel_hi:[1,0]
	v_pk_mul_f32 v[42:43], v[32:33], v[42:43]
	v_pk_mul_f32 v[44:45], v[30:31], v[44:45]
	v_pk_fma_f32 v[36:37], v[40:41], v[42:43], v[156:157]
	v_pk_fma_f32 v[34:35], v[38:39], v[44:45], v[154:155]
	s_nop 0
	v_cvt_pk_bf16_f32 v34, v34, v35
	v_cvt_pk_bf16_f32 v35, v36, v37
	global_store_dwordx2 v[90:91], v[34:35], off offset:3584
	s_cbranch_scc0 .Lnh0_exit
	s_cmpk_gt_i32 s4, 0x1fff
	s_cbranch_scc1 .LBB0_461
.Lnh0_B:
	s_add_i32 s5, s4, 0xffffe000
	s_ashr_i32 s5, s5, 10
	s_add_i32 s5, s5, 1
	s_cmpk_gt_i32 s4, 0x1fff
	v_lshl_add_u64 v[34:35], s[6:7], 0, v[102:103]
	s_cselect_b32 s5, s5, 0
	v_add_co_u32_e32 v34, vcc, 0x27a00000, v34
	v_mad_i64_i32 v[36:37], s[8:9], s5, v245, v[98:99]
	s_nop 0
	v_addc_co_u32_e32 v35, vcc, 0, v35, vcc
	v_add_co_u32_e32 v70, vcc, 0x2000, v36
	s_nop 1
	v_addc_co_u32_e32 v71, vcc, 0, v37, vcc
	global_load_dwordx2 v[114:115], v[34:35], off
	global_load_dwordx2 v[116:117], v[34:35], off offset:512
	global_load_dwordx2 v[120:121], v[34:35], off offset:1024
	global_load_dwordx2 v[104:105], v[34:35], off offset:1536
	v_add_co_u32_e32 v38, vcc, s97, v36
	s_nop 1
	v_addc_co_u32_e32 v39, vcc, 0, v37, vcc
	v_add_co_u32_e32 v40, vcc, s91, v36
	s_nop 1
	v_addc_co_u32_e32 v41, vcc, 0, v37, vcc
	global_load_dwordx2 v[122:123], v[34:35], off offset:2048
	global_load_dwordx2 v[146:147], v[34:35], off offset:2560
	global_load_dwordx2 v[148:149], v[34:35], off offset:3072
	global_load_dwordx2 v[108:109], v[34:35], off offset:3584
	s_nop 0
	s_nop 0
	s_nop 0
	s_nop 0
	s_waitcnt vmcnt(4)
	v_lshlrev_b32_e32 v113, 16, v104
	v_and_b32_e32 v111, 0xffff0000, v104
	v_lshlrev_b32_e32 v118, 16, v105
	v_and_b32_e32 v119, 0xffff0000, v105
	s_waitcnt vmcnt(0)
	v_lshlrev_b32_e32 v107, 16, v108
	v_and_b32_e32 v105, 0xffff0000, v108
	v_lshlrev_b32_e32 v108, 16, v109
	v_and_b32_e32 v109, 0xffff0000, v109
	v_and_b32_e32 v139, 0xffff0000, v115
	v_and_b32_e32 v137, 0xffff0000, v114
	v_lshlrev_b32_e32 v138, 16, v115
	v_mul_f32_e32 v0, v139, v139
	v_lshlrev_b32_e32 v136, 16, v114
	v_pk_fma_f32 v[114:115], v[138:139], v[138:139], v[0:1] op_sel_hi:[1,1,0]
	v_and_b32_e32 v135, 0xffff0000, v117
	v_and_b32_e32 v134, 0xffff0000, v116
	v_mul_f32_e32 v0, v137, v137
	v_lshlrev_b32_e32 v133, 16, v117
	v_lshlrev_b32_e32 v132, 16, v116
	v_pk_mul_f32 v[116:117], v[134:135], v[134:135]
	v_lshlrev_b32_e32 v128, 16, v120
	v_and_b32_e32 v129, 0xffff0000, v120
	v_lshlrev_b32_e32 v130, 16, v121
	v_and_b32_e32 v131, 0xffff0000, v121
	v_pk_fma_f32 v[120:121], v[136:137], v[136:137], v[0:1] op_sel_hi:[1,1,0]
	v_pk_fma_f32 v[116:117], v[132:133], v[132:133], v[116:117]
	v_mov_b32_e32 v112, v120
	v_mov_b32_e32 v124, v114
	v_mov_b32_e32 v125, v113
	v_mul_f32_e32 v104, v111, v111
	v_pk_add_f32 v[114:115], v[120:121], v[114:115]
	v_pk_mul_f32 v[120:121], v[112:113], v[124:125]
	v_pk_add_f32 v[116:117], v[116:117], v[116:117] op_sel:[0,1] op_sel_hi:[1,0]
	v_mov_b32_e32 v115, v121
	v_mov_b32_e32 v117, v104
	v_mul_f32_e32 v0, v129, v129
	v_pk_add_f32 v[114:115], v[114:115], v[116:117]
	v_pk_fma_f32 v[116:117], v[128:129], v[128:129], v[0:1] op_sel_hi:[1,1,0]
	v_mul_f32_e32 v0, v131, v131
	v_mul_f32_e32 v106, v118, v118
	v_mul_f32_e32 v110, v119, v119
	v_pk_fma_f32 v[120:121], v[130:131], v[130:131], v[0:1] op_sel_hi:[1,1,0]
	v_mov_b32_e32 v117, v106
	v_mov_b32_e32 v121, v110
	v_pk_add_f32 v[116:117], v[116:117], v[120:121]
	v_and_b32_e32 v127, 0xffff0000, v123
	v_and_b32_e32 v126, 0xffff0000, v122
	v_pk_add_f32 v[150:151], v[114:115], v[116:117]
	v_lshlrev_b32_e32 v125, 16, v123
	v_lshlrev_b32_e32 v124, 16, v122
	v_pk_mul_f32 v[114:115], v[126:127], v[126:127]
	v_and_b32_e32 v123, 0xffff0000, v147
	v_pk_fma_f32 v[114:115], v[124:125], v[124:125], v[114:115]
	v_and_b32_e32 v122, 0xffff0000, v146
	v_pk_add_f32 v[152:153], v[114:115], v[114:115] op_sel:[0,1] op_sel_hi:[1,0]
	v_lshlrev_b32_e32 v121, 16, v147
	v_lshlrev_b32_e32 v120, 16, v146
	v_pk_mul_f32 v[114:115], v[122:123], v[122:123]
	v_lshlrev_b32_e32 v116, 16, v149
	v_pk_fma_f32 v[146:147], v[120:121], v[120:121], v[114:115]
	v_lshlrev_b32_e32 v114, 16, v148
	v_and_b32_e32 v115, 0xffff0000, v148
	v_and_b32_e32 v117, 0xffff0000, v149
	v_pk_add_f32 v[148:149], v[150:151], v[150:151] op_sel:[0,1] op_sel_hi:[1,0]
	v_mov_b32_e32 v150, v152
	v_mov_b32_e32 v106, v148
	v_mov_b32_e32 v151, v107
	v_mul_f32_e32 v0, v105, v105
	v_pk_add_f32 v[148:149], v[148:149], v[152:153]
	v_pk_mul_f32 v[150:151], v[106:107], v[150:151]
	v_pk_add_f32 v[146:147], v[146:147], v[146:147] op_sel:[0,1] op_sel_hi:[1,0]
	v_mov_b32_e32 v149, v151
	v_mov_b32_e32 v147, v0
	v_mul_f32_e32 v0, v115, v115
	v_pk_add_f32 v[146:147], v[148:149], v[146:147]
	v_pk_fma_f32 v[148:149], v[114:115], v[114:115], v[0:1] op_sel_hi:[1,1,0]
	v_mul_f32_e32 v0, v117, v117
	v_mul_f32_e32 v104, v108, v108
	v_mul_f32_e32 v110, v109, v109
	v_pk_fma_f32 v[150:151], v[116:117], v[116:117], v[0:1] op_sel_hi:[1,1,0]
	v_mov_b32_e32 v149, v104
	v_mov_b32_e32 v151, v110
	v_pk_add_f32 v[148:149], v[148:149], v[150:151]
	v_pk_add_f32 v[94:95], v[214:215], 1.0 op_sel_hi:[1,0]
	v_pk_add_f32 v[146:147], v[146:147], v[148:149]
	v_pk_add_f32 v[96:97], v[216:217], 1.0 op_sel_hi:[1,0]
	v_add_f32_e32 v0, v146, v147
	v_lshl_add_u64 v[146:147], s[6:7], 0, v[100:101]
	v_pk_add_f32 v[88:89], v[208:209], 1.0 op_sel_hi:[1,0]
	v_pk_add_f32 v[86:87], v[206:207], 1.0 op_sel_hi:[1,0]
	v_pk_add_f32 v[80:81], v[200:201], 1.0 op_sel_hi:[1,0]
	s_nop 1
	v_add_f32_dpp v0, v0, v0 quad_perm:[1,0,3,2] row_mask:0xf bank_mask:0xf
	v_pk_add_f32 v[78:79], v[198:199], 1.0 op_sel_hi:[1,0]
	v_mov_b32_e32 v110, v113
	v_pk_add_f32 v[72:73], v[192:193], 1.0 op_sel_hi:[1,0]
	v_pk_add_f32 v[70:71], v[190:191], 1.0 op_sel_hi:[1,0]
	s_nop 1
	v_add_f32_dpp v0, v0, v0 quad_perm:[2,3,0,1] row_mask:0xf bank_mask:0xf
	v_pk_add_f32 v[64:65], v[184:185], 1.0 op_sel_hi:[1,0]
	v_pk_add_f32 v[62:63], v[182:183], 1.0 op_sel_hi:[1,0]
	v_pk_add_f32 v[56:57], v[176:177], 1.0 op_sel_hi:[1,0]
	v_pk_add_f32 v[54:55], v[174:175], 1.0 op_sel_hi:[1,0]
	s_nop 1
	v_add_f32_dpp v0, v0, v0 row_half_mirror row_mask:0xf bank_mask:0xf
	v_pk_add_f32 v[48:49], v[168:169], 1.0 op_sel_hi:[1,0]
	v_pk_add_f32 v[46:47], v[166:167], 1.0 op_sel_hi:[1,0]
	v_readlane_b32 s8, v254, 13
	s_add_i32 s4, s4, s8
	s_nop 1
	v_add_f32_dpp v0, v0, v0 row_mirror row_mask:0xf bank_mask:0xf
	v_pk_add_f32 v[40:41], v[160:161], 1.0 op_sel_hi:[1,0]
	v_pk_add_f32 v[38:39], v[158:159], 1.0 op_sel_hi:[1,0]
	s_add_u32 s6, s6, s86
	s_addc_u32 s7, s7, s87
	v_mov_b32_e32 v104, v0
	s_nop 1
	v_permlane16_swap_b32 v0, v104
	v_add_f32_e32 v0, v0, v104
	s_cmpk_lt_i32 s4, 0x2800
	v_readlane_b32 s9, v254, 14
	v_mov_b32_e32 v104, v0
	s_nop 1
	v_permlane32_swap_b32 v0, v104
	v_add_f32_e32 v0, v0, v104
	v_fmamk_f32 v0, v0, 0x3a000000, v224
	v_rsq_f32_e32 v0, v0
	v_mov_b32_e32 v104, v107
	v_pk_mul_f32 v[136:137], v[0:1], v[136:137] op_sel_hi:[0,1]
	v_pk_mul_f32 v[138:139], v[0:1], v[138:139] op_sel_hi:[0,1]
	v_pk_mul_f32 v[136:137], v[2:3], v[136:137]
	v_pk_mul_f32 v[138:139], v[4:5], v[138:139]
	v_pk_fma_f32 v[90:91], v[94:95], v[136:137], v[210:211]
	v_pk_fma_f32 v[92:93], v[96:97], v[138:139], v[212:213]
	v_cvt_pk_bf16_f32 v94, v90, v91
	v_add_co_u32_e32 v90, vcc, s51, v146
	v_cvt_pk_bf16_f32 v95, v92, v93
	s_nop 0
	v_addc_co_u32_e32 v91, vcc, 0, v147, vcc
	v_mov_b32_e32 v92, v133
	v_mov_b32_e32 v93, v135
	v_mov_b32_e32 v133, v134
	global_store_dwordx2 v[90:91], v[94:95], off
	v_pk_mul_f32 v[92:93], v[0:1], v[92:93] op_sel_hi:[0,1]
	v_pk_mul_f32 v[94:95], v[0:1], v[132:133] op_sel_hi:[0,1]
	v_pk_mul_f32 v[94:95], v[6:7], v[94:95]
	v_pk_mul_f32 v[92:93], v[8:9], v[92:93]
	v_pk_fma_f32 v[82:83], v[86:87], v[94:95], v[202:203]
	v_pk_fma_f32 v[84:85], v[88:89], v[92:93], v[204:205]
	v_cvt_pk_bf16_f32 v82, v82, v83
	v_cvt_pk_bf16_f32 v83, v84, v85
	global_store_dwordx2 v[90:91], v[82:83], off offset:512
	v_pk_mul_f32 v[82:83], v[0:1], v[130:131] op_sel_hi:[0,1]
	v_pk_mul_f32 v[84:85], v[0:1], v[128:129] op_sel_hi:[0,1]
	v_pk_mul_f32 v[84:85], v[10:11], v[84:85]
	v_pk_mul_f32 v[82:83], v[12:13], v[82:83]
	v_pk_fma_f32 v[74:75], v[78:79], v[84:85], v[194:195]
	v_pk_fma_f32 v[76:77], v[80:81], v[82:83], v[196:197]
	v_cvt_pk_bf16_f32 v74, v74, v75
	v_cvt_pk_bf16_f32 v75, v76, v77
	global_store_dwordx2 v[90:91], v[74:75], off offset:1024
	v_pk_mul_f32 v[74:75], v[118:119], v[0:1] op_sel_hi:[1,0]
	v_pk_mul_f32 v[76:77], v[110:111], v[0:1] op_sel_hi:[1,0]
	v_pk_mul_f32 v[74:75], v[16:17], v[74:75]
	v_pk_mul_f32 v[76:77], v[14:15], v[76:77]
	v_pk_fma_f32 v[68:69], v[72:73], v[74:75], v[188:189]
	v_pk_fma_f32 v[66:67], v[70:71], v[76:77], v[186:187]
	s_nop 0
	v_cvt_pk_bf16_f32 v66, v66, v67
	v_cvt_pk_bf16_f32 v67, v68, v69
	global_store_dwordx2 v[90:91], v[66:67], off offset:1536
	v_mov_b32_e32 v66, v125
	v_mov_b32_e32 v67, v127
	v_mov_b32_e32 v125, v126
	v_pk_mul_f32 v[66:67], v[0:1], v[66:67] op_sel_hi:[0,1]
	v_pk_mul_f32 v[68:69], v[0:1], v[124:125] op_sel_hi:[0,1]
	v_pk_mul_f32 v[68:69], v[18:19], v[68:69]
	v_pk_mul_f32 v[66:67], v[20:21], v[66:67]
	v_pk_fma_f32 v[58:59], v[62:63], v[68:69], v[178:179]
	v_pk_fma_f32 v[60:61], v[64:65], v[66:67], v[180:181]
	v_cvt_pk_bf16_f32 v58, v58, v59
	v_cvt_pk_bf16_f32 v59, v60, v61
	global_store_dwordx2 v[90:91], v[58:59], off offset:2048
	v_mov_b32_e32 v58, v121
	v_mov_b32_e32 v59, v123
	v_mov_b32_e32 v121, v122
	v_pk_mul_f32 v[58:59], v[0:1], v[58:59] op_sel_hi:[0,1]
	v_pk_mul_f32 v[60:61], v[0:1], v[120:121] op_sel_hi:[0,1]
	v_pk_mul_f32 v[60:61], v[22:23], v[60:61]
	v_pk_mul_f32 v[58:59], v[24:25], v[58:59]
	v_pk_fma_f32 v[50:51], v[54:55], v[60:61], v[170:171]
	v_pk_fma_f32 v[52:53], v[56:57], v[58:59], v[172:173]
	v_cvt_pk_bf16_f32 v50, v50, v51
	v_cvt_pk_bf16_f32 v51, v52, v53
	global_store_dwordx2 v[90:91], v[50:51], off offset:2560
	v_pk_mul_f32 v[50:51], v[0:1], v[116:117] op_sel_hi:[0,1]
	v_pk_mul_f32 v[52:53], v[0:1], v[114:115] op_sel_hi:[0,1]
	v_pk_mul_f32 v[52:53], v[26:27], v[52:53]
	v_pk_mul_f32 v[50:51], v[28:29], v[50:51]
	v_pk_fma_f32 v[42:43], v[46:47], v[52:53], v[162:163]
	v_pk_fma_f32 v[44:45], v[48:49], v[50:51], v[164:165]
	v_cvt_pk_bf16_f32 v42, v42, v43
	v_cvt_pk_bf16_f32 v43, v44, v45
	global_store_dwordx2 v[90:91], v[42:43], off offset:3072
	v_pk_mul_f32 v[42:43], v[108:109], v[0:1] op_sel_hi:[1,0]
	v_pk_mul_f32 v[44:45], v[104:105], v[0:1] op_sel_hi:[1,0]
	v_pk_mul_f32 v[42:43], v[32:33], v[42:43]
	v_pk_mul_f32 v[44:45], v[30:31], v[44:45]
	v_pk_fma_f32 v[36:37], v[40:41], v[42:43], v[156:157]
	v_pk_fma_f32 v[34:35], v[38:39], v[44:45], v[154:155]
	s_nop 0
	v_cvt_pk_bf16_f32 v34, v34, v35
	v_cvt_pk_bf16_f32 v35, v36, v37
	global_store_dwordx2 v[90:91], v[34:35], off offset:3584
	s_cbranch_scc0 .Lnh0_exit
	s_cmpk_gt_i32 s4, 0x1fff
	s_cbranch_scc1 .LBB0_461
	s_branch .Lnh0_B
.Lnh0_exit:
.LBB0_462:
	s_waitcnt vmcnt(0)
	s_barrier
	v_mbcnt_lo_u32_b32 v0, -1, 0
	v_mbcnt_hi_u32_b32 v0, -1, v0
	s_nop 0
	v_sub_u32_e32 v0, 0, v0
	v_cmp_eq_u32_e32 vcc, s81, v0
	s_and_saveexec_b64 s[36:37], vcc
	s_cbranch_execz .LBB0_506
	v_readlane_b32 s38, v252, 13
	v_readlane_b32 s4, v254, 9
	v_readlane_b32 s39, v252, 14
	v_readlane_b32 s40, v252, 15
	v_mov_b32_e32 v0, s4
	s_waitcnt vmcnt(0) expcnt(0) lgkmcnt(0)
	ds_read_b32 v2, v0
	v_readlane_b32 s4, v254, 10
	s_waitcnt lgkmcnt(0)
	v_cmp_ne_u32_e32 vcc, 0, v2
	v_mov_b32_e32 v0, s4
	ds_read_b32 v0, v0
	s_cbranch_vccnz .LBB0_477
	v_readlane_b32 s4, v252, 10
	v_readlane_b32 s5, v252, 11
	s_load_dwordx2 s[8:9], s[4:5], 0x4
	s_add_u32 s4, s38, 0x1000
	s_addc_u32 s5, s39, 0
	s_add_u32 s6, s38, 0x1100
	s_addc_u32 s7, s39, 0
	s_waitcnt lgkmcnt(0)
	s_mul_i32 s30, s8, s3
	s_add_u32 s8, s38, 0x1200
	s_mul_i32 s30, s30, s9
	s_addc_u32 s9, s39, 0
	s_add_u32 s10, s38, 0x1300
	s_addc_u32 s11, s39, 0
	s_mov_b32 s31, 1
	s_mov_b64 s[12:13], 0
	s_branch .LBB0_467

.LBB0_992:
	s_add_i32 s4, s8, 0xffffe000
	s_ashr_i32 s4, s4, 10
	s_add_i32 s4, s4, 1
	s_cmpk_gt_i32 s8, 0x1fff
	v_lshl_add_u64 v[34:35], s[10:11], 0, v[102:103]
	s_cselect_b32 s4, s4, 0
	v_add_co_u32_e32 v34, vcc, 0x27a00000, v34
	v_mad_i64_i32 v[36:37], s[4:5], s4, v245, v[98:99]
	s_nop 0
	v_addc_co_u32_e32 v35, vcc, 0, v35, vcc
	v_add_co_u32_e32 v70, vcc, 0x2000, v36
	s_nop 1
	v_addc_co_u32_e32 v71, vcc, 0, v37, vcc
	global_load_dwordx4 v[210:213], v[36:37], off
	global_load_dwordx4 v[202:205], v[36:37], off offset:1024
	global_load_dwordx4 v[214:217], v[70:71], off
	global_load_dwordx4 v[206:209], v[70:71], off offset:1024
	global_load_dwordx2 v[114:115], v[34:35], off
	global_load_dwordx2 v[116:117], v[34:35], off offset:512
	global_load_dwordx2 v[120:121], v[34:35], off offset:1024
	global_load_dwordx2 v[104:105], v[34:35], off offset:1536
	global_load_dwordx4 v[194:197], v[36:37], off offset:2048
	global_load_dwordx4 v[186:189], v[36:37], off offset:3072
	v_add_co_u32_e32 v38, vcc, s97, v36
	s_nop 1
	v_addc_co_u32_e32 v39, vcc, 0, v37, vcc
	v_add_co_u32_e32 v40, vcc, s91, v36
	s_nop 1
	v_addc_co_u32_e32 v41, vcc, 0, v37, vcc
	global_load_dwordx4 v[178:181], v[38:39], off
	global_load_dwordx4 v[170:173], v[38:39], off offset:1024
	global_load_dwordx4 v[182:185], v[40:41], off
	global_load_dwordx4 v[174:177], v[40:41], off offset:1024
	global_load_dwordx2 v[122:123], v[34:35], off offset:2048
	global_load_dwordx2 v[146:147], v[34:35], off offset:2560
	global_load_dwordx2 v[148:149], v[34:35], off offset:3072
	global_load_dwordx2 v[108:109], v[34:35], off offset:3584
	global_load_dwordx4 v[162:165], v[38:39], off offset:2048
	s_nop 0
	global_load_dwordx4 v[154:157], v[38:39], off offset:3072
	global_load_dwordx4 v[166:169], v[40:41], off offset:2048
	s_nop 0
	global_load_dwordx4 v[158:161], v[40:41], off offset:3072
	s_nop 0
	global_load_dwordx4 v[198:201], v[70:71], off offset:2048
	s_nop 0
	global_load_dwordx4 v[190:193], v[70:71], off offset:3072
	s_waitcnt vmcnt(14)
	v_lshlrev_b32_e32 v113, 16, v104
	v_and_b32_e32 v111, 0xffff0000, v104
	v_lshlrev_b32_e32 v118, 16, v105
	v_and_b32_e32 v119, 0xffff0000, v105
	s_waitcnt vmcnt(6)
	v_lshlrev_b32_e32 v107, 16, v108
	v_and_b32_e32 v105, 0xffff0000, v108
	v_lshlrev_b32_e32 v108, 16, v109
	v_and_b32_e32 v109, 0xffff0000, v109
	v_and_b32_e32 v139, 0xffff0000, v115
	v_and_b32_e32 v137, 0xffff0000, v114
	v_lshlrev_b32_e32 v138, 16, v115
	v_mul_f32_e32 v0, v139, v139
	v_lshlrev_b32_e32 v136, 16, v114
	v_pk_fma_f32 v[114:115], v[138:139], v[138:139], v[0:1] op_sel_hi:[1,1,0]
	v_and_b32_e32 v135, 0xffff0000, v117
	v_and_b32_e32 v134, 0xffff0000, v116
	v_mul_f32_e32 v0, v137, v137
	v_lshlrev_b32_e32 v133, 16, v117
	v_lshlrev_b32_e32 v132, 16, v116
	v_pk_mul_f32 v[116:117], v[134:135], v[134:135]
	v_lshlrev_b32_e32 v128, 16, v120
	v_and_b32_e32 v129, 0xffff0000, v120
	v_lshlrev_b32_e32 v130, 16, v121
	v_and_b32_e32 v131, 0xffff0000, v121
	v_pk_fma_f32 v[120:121], v[136:137], v[136:137], v[0:1] op_sel_hi:[1,1,0]
	v_pk_fma_f32 v[116:117], v[132:133], v[132:133], v[116:117]
	v_mov_b32_e32 v112, v120
	v_mov_b32_e32 v124, v114
	v_mov_b32_e32 v125, v113
	v_mul_f32_e32 v104, v111, v111
	v_pk_add_f32 v[114:115], v[120:121], v[114:115]
	v_pk_mul_f32 v[120:121], v[112:113], v[124:125]
	v_pk_add_f32 v[116:117], v[116:117], v[116:117] op_sel:[0,1] op_sel_hi:[1,0]
	v_mov_b32_e32 v115, v121
	v_mov_b32_e32 v117, v104
	v_mul_f32_e32 v0, v129, v129
	v_pk_add_f32 v[114:115], v[114:115], v[116:117]
	v_pk_fma_f32 v[116:117], v[128:129], v[128:129], v[0:1] op_sel_hi:[1,1,0]
	v_mul_f32_e32 v0, v131, v131
	v_mul_f32_e32 v106, v118, v118
	v_mul_f32_e32 v110, v119, v119
	v_pk_fma_f32 v[120:121], v[130:131], v[130:131], v[0:1] op_sel_hi:[1,1,0]
	v_mov_b32_e32 v117, v106
	v_mov_b32_e32 v121, v110
	v_pk_add_f32 v[116:117], v[116:117], v[120:121]
	v_and_b32_e32 v127, 0xffff0000, v123
	v_and_b32_e32 v126, 0xffff0000, v122
	v_pk_add_f32 v[150:151], v[114:115], v[116:117]
	v_lshlrev_b32_e32 v125, 16, v123
	v_lshlrev_b32_e32 v124, 16, v122
	v_pk_mul_f32 v[114:115], v[126:127], v[126:127]
	v_and_b32_e32 v123, 0xffff0000, v147
	v_pk_fma_f32 v[114:115], v[124:125], v[124:125], v[114:115]
	v_and_b32_e32 v122, 0xffff0000, v146
	v_pk_add_f32 v[152:153], v[114:115], v[114:115] op_sel:[0,1] op_sel_hi:[1,0]
	v_lshlrev_b32_e32 v121, 16, v147
	v_lshlrev_b32_e32 v120, 16, v146
	v_pk_mul_f32 v[114:115], v[122:123], v[122:123]
	v_lshlrev_b32_e32 v116, 16, v149
	v_pk_fma_f32 v[146:147], v[120:121], v[120:121], v[114:115]
	v_lshlrev_b32_e32 v114, 16, v148
	v_and_b32_e32 v115, 0xffff0000, v148
	v_and_b32_e32 v117, 0xffff0000, v149
	v_pk_add_f32 v[148:149], v[150:151], v[150:151] op_sel:[0,1] op_sel_hi:[1,0]
	v_mov_b32_e32 v150, v152
	v_mov_b32_e32 v106, v148
	v_mov_b32_e32 v151, v107
	v_mul_f32_e32 v0, v105, v105
	v_pk_add_f32 v[148:149], v[148:149], v[152:153]
	v_pk_mul_f32 v[150:151], v[106:107], v[150:151]
	v_pk_add_f32 v[146:147], v[146:147], v[146:147] op_sel:[0,1] op_sel_hi:[1,0]
	v_mov_b32_e32 v149, v151
	v_mov_b32_e32 v147, v0
	v_mul_f32_e32 v0, v115, v115
	v_pk_add_f32 v[146:147], v[148:149], v[146:147]
	v_pk_fma_f32 v[148:149], v[114:115], v[114:115], v[0:1] op_sel_hi:[1,1,0]
	v_mul_f32_e32 v0, v117, v117
	v_mul_f32_e32 v104, v108, v108
	v_mul_f32_e32 v110, v109, v109
	v_pk_fma_f32 v[150:151], v[116:117], v[116:117], v[0:1] op_sel_hi:[1,1,0]
	v_mov_b32_e32 v149, v104
	v_mov_b32_e32 v151, v110
	v_pk_add_f32 v[148:149], v[148:149], v[150:151]
	v_pk_add_f32 v[94:95], v[214:215], 1.0 op_sel_hi:[1,0]
	v_pk_add_f32 v[146:147], v[146:147], v[148:149]
	v_pk_add_f32 v[96:97], v[216:217], 1.0 op_sel_hi:[1,0]
	v_add_f32_e32 v0, v146, v147
	v_lshl_add_u64 v[146:147], s[10:11], 0, v[100:101]
	v_pk_add_f32 v[88:89], v[208:209], 1.0 op_sel_hi:[1,0]
	v_pk_add_f32 v[86:87], v[206:207], 1.0 op_sel_hi:[1,0]
	s_waitcnt vmcnt(1)
	v_pk_add_f32 v[80:81], v[200:201], 1.0 op_sel_hi:[1,0]
	s_nop 1
	v_add_f32_dpp v0, v0, v0 quad_perm:[1,0,3,2] row_mask:0xf bank_mask:0xf
	v_pk_add_f32 v[78:79], v[198:199], 1.0 op_sel_hi:[1,0]
	v_mov_b32_e32 v110, v113
	s_waitcnt vmcnt(0)
	v_pk_add_f32 v[72:73], v[192:193], 1.0 op_sel_hi:[1,0]
	v_pk_add_f32 v[70:71], v[190:191], 1.0 op_sel_hi:[1,0]
	s_nop 1
	v_add_f32_dpp v0, v0, v0 quad_perm:[2,3,0,1] row_mask:0xf bank_mask:0xf
	v_pk_add_f32 v[64:65], v[184:185], 1.0 op_sel_hi:[1,0]
	v_pk_add_f32 v[62:63], v[182:183], 1.0 op_sel_hi:[1,0]
	v_pk_add_f32 v[56:57], v[176:177], 1.0 op_sel_hi:[1,0]
	v_pk_add_f32 v[54:55], v[174:175], 1.0 op_sel_hi:[1,0]
	s_nop 1
	v_add_f32_dpp v0, v0, v0 row_half_mirror row_mask:0xf bank_mask:0xf
	v_pk_add_f32 v[48:49], v[168:169], 1.0 op_sel_hi:[1,0]
	v_pk_add_f32 v[46:47], v[166:167], 1.0 op_sel_hi:[1,0]
	v_readlane_b32 s4, v254, 13
	s_add_i32 s8, s8, s4
	s_nop 1
	v_add_f32_dpp v0, v0, v0 row_mirror row_mask:0xf bank_mask:0xf
	v_pk_add_f32 v[40:41], v[160:161], 1.0 op_sel_hi:[1,0]
	v_pk_add_f32 v[38:39], v[158:159], 1.0 op_sel_hi:[1,0]
	s_add_u32 s10, s10, s86
	s_addc_u32 s11, s11, s87
	v_mov_b32_e32 v104, v0
	s_nop 1
	v_permlane16_swap_b32 v0, v104
	v_add_f32_e32 v0, v0, v104
	s_cmpk_lt_i32 s8, 0x2800
	v_readlane_b32 s5, v254, 14
	v_mov_b32_e32 v104, v0
	s_nop 1
	v_permlane32_swap_b32 v0, v104
	v_add_f32_e32 v0, v0, v104
	v_fmamk_f32 v0, v0, 0x3a000000, v224
	v_rsq_f32_e32 v0, v0
	v_mov_b32_e32 v104, v107
	v_pk_mul_f32 v[136:137], v[0:1], v[136:137] op_sel_hi:[0,1]
	v_pk_mul_f32 v[138:139], v[0:1], v[138:139] op_sel_hi:[0,1]
	v_pk_mul_f32 v[136:137], v[10:11], v[136:137]
	v_pk_mul_f32 v[138:139], v[12:13], v[138:139]
	v_pk_fma_f32 v[90:91], v[94:95], v[136:137], v[210:211]
	v_pk_fma_f32 v[92:93], v[96:97], v[138:139], v[212:213]
	v_cvt_pk_bf16_f32 v94, v90, v91
	v_add_co_u32_e32 v90, vcc, s51, v146
	v_cvt_pk_bf16_f32 v95, v92, v93
	s_nop 0
	v_addc_co_u32_e32 v91, vcc, 0, v147, vcc
	v_mov_b32_e32 v92, v133
	v_mov_b32_e32 v93, v135
	v_mov_b32_e32 v133, v134
	global_store_dwordx2 v[90:91], v[94:95], off
	v_pk_mul_f32 v[92:93], v[0:1], v[92:93] op_sel_hi:[0,1]
	v_pk_mul_f32 v[94:95], v[0:1], v[132:133] op_sel_hi:[0,1]
	v_pk_mul_f32 v[94:95], v[2:3], v[94:95]
	v_pk_mul_f32 v[92:93], v[4:5], v[92:93]
	v_pk_fma_f32 v[82:83], v[86:87], v[94:95], v[202:203]
	v_pk_fma_f32 v[84:85], v[88:89], v[92:93], v[204:205]
	v_cvt_pk_bf16_f32 v82, v82, v83
	v_cvt_pk_bf16_f32 v83, v84, v85
	global_store_dwordx2 v[90:91], v[82:83], off offset:512
	v_pk_mul_f32 v[82:83], v[0:1], v[130:131] op_sel_hi:[0,1]
	v_pk_mul_f32 v[84:85], v[0:1], v[128:129] op_sel_hi:[0,1]
	v_pk_mul_f32 v[84:85], v[6:7], v[84:85]
	v_pk_mul_f32 v[82:83], v[8:9], v[82:83]
	v_pk_fma_f32 v[74:75], v[78:79], v[84:85], v[194:195]
	v_pk_fma_f32 v[76:77], v[80:81], v[82:83], v[196:197]
	v_cvt_pk_bf16_f32 v74, v74, v75
	v_cvt_pk_bf16_f32 v75, v76, v77
	global_store_dwordx2 v[90:91], v[74:75], off offset:1024
	v_pk_mul_f32 v[74:75], v[118:119], v[0:1] op_sel_hi:[1,0]
	v_pk_mul_f32 v[76:77], v[110:111], v[0:1] op_sel_hi:[1,0]
	v_pk_mul_f32 v[74:75], v[16:17], v[74:75]
	v_pk_mul_f32 v[76:77], v[14:15], v[76:77]
	v_pk_fma_f32 v[68:69], v[72:73], v[74:75], v[188:189]
	v_pk_fma_f32 v[66:67], v[70:71], v[76:77], v[186:187]
	s_nop 0
	v_cvt_pk_bf16_f32 v66, v66, v67
	v_cvt_pk_bf16_f32 v67, v68, v69
	global_store_dwordx2 v[90:91], v[66:67], off offset:1536
	v_mov_b32_e32 v66, v125
	v_mov_b32_e32 v67, v127
	v_mov_b32_e32 v125, v126
	v_pk_mul_f32 v[66:67], v[0:1], v[66:67] op_sel_hi:[0,1]
	v_pk_mul_f32 v[68:69], v[0:1], v[124:125] op_sel_hi:[0,1]
	v_pk_mul_f32 v[68:69], v[18:19], v[68:69]
	v_pk_mul_f32 v[66:67], v[20:21], v[66:67]
	v_pk_fma_f32 v[58:59], v[62:63], v[68:69], v[178:179]
	v_pk_fma_f32 v[60:61], v[64:65], v[66:67], v[180:181]
	v_cvt_pk_bf16_f32 v58, v58, v59
	v_cvt_pk_bf16_f32 v59, v60, v61
	global_store_dwordx2 v[90:91], v[58:59], off offset:2048
	v_mov_b32_e32 v58, v121
	v_mov_b32_e32 v59, v123
	v_mov_b32_e32 v121, v122
	v_pk_mul_f32 v[58:59], v[0:1], v[58:59] op_sel_hi:[0,1]
	v_pk_mul_f32 v[60:61], v[0:1], v[120:121] op_sel_hi:[0,1]
	v_pk_mul_f32 v[60:61], v[22:23], v[60:61]
	v_pk_mul_f32 v[58:59], v[24:25], v[58:59]
	v_pk_fma_f32 v[50:51], v[54:55], v[60:61], v[170:171]
	v_pk_fma_f32 v[52:53], v[56:57], v[58:59], v[172:173]
	v_cvt_pk_bf16_f32 v50, v50, v51
	v_cvt_pk_bf16_f32 v51, v52, v53
	global_store_dwordx2 v[90:91], v[50:51], off offset:2560
	v_pk_mul_f32 v[50:51], v[0:1], v[116:117] op_sel_hi:[0,1]
	v_pk_mul_f32 v[52:53], v[0:1], v[114:115] op_sel_hi:[0,1]
	v_pk_mul_f32 v[52:53], v[26:27], v[52:53]
	v_pk_mul_f32 v[50:51], v[28:29], v[50:51]
	v_pk_fma_f32 v[42:43], v[46:47], v[52:53], v[162:163]
	v_pk_fma_f32 v[44:45], v[48:49], v[50:51], v[164:165]
	v_cvt_pk_bf16_f32 v42, v42, v43
	v_cvt_pk_bf16_f32 v43, v44, v45
	global_store_dwordx2 v[90:91], v[42:43], off offset:3072
	v_pk_mul_f32 v[42:43], v[108:109], v[0:1] op_sel_hi:[1,0]
	v_pk_mul_f32 v[44:45], v[104:105], v[0:1] op_sel_hi:[1,0]
	v_pk_mul_f32 v[42:43], v[32:33], v[42:43]
	v_pk_mul_f32 v[44:45], v[30:31], v[44:45]
	v_pk_fma_f32 v[36:37], v[40:41], v[42:43], v[156:157]
	v_pk_fma_f32 v[34:35], v[38:39], v[44:45], v[154:155]
	s_nop 0
	v_cvt_pk_bf16_f32 v34, v34, v35
	v_cvt_pk_bf16_f32 v35, v36, v37
	global_store_dwordx2 v[90:91], v[34:35], off offset:3584
	s_cbranch_scc0 .Lnh1_exit
	s_cmpk_gt_i32 s8, 0x1fff
	s_cbranch_scc1 .LBB0_992
.Lnh1_B:
	s_add_i32 s4, s8, 0xffffe000
	s_ashr_i32 s4, s4, 10
	s_add_i32 s4, s4, 1
	s_cmpk_gt_i32 s8, 0x1fff
	v_lshl_add_u64 v[34:35], s[10:11], 0, v[102:103]
	s_cselect_b32 s4, s4, 0
	v_add_co_u32_e32 v34, vcc, 0x27a00000, v34
	v_mad_i64_i32 v[36:37], s[4:5], s4, v245, v[98:99]
	s_nop 0
	v_addc_co_u32_e32 v35, vcc, 0, v35, vcc
	v_add_co_u32_e32 v70, vcc, 0x2000, v36
	s_nop 1
	v_addc_co_u32_e32 v71, vcc, 0, v37, vcc
	global_load_dwordx2 v[114:115], v[34:35], off
	global_load_dwordx2 v[116:117], v[34:35], off offset:512
	global_load_dwordx2 v[120:121], v[34:35], off offset:1024
	global_load_dwordx2 v[104:105], v[34:35], off offset:1536
	v_add_co_u32_e32 v38, vcc, s97, v36
	s_nop 1
	v_addc_co_u32_e32 v39, vcc, 0, v37, vcc
	v_add_co_u32_e32 v40, vcc, s91, v36
	s_nop 1
	v_addc_co_u32_e32 v41, vcc, 0, v37, vcc
	global_load_dwordx2 v[122:123], v[34:35], off offset:2048
	global_load_dwordx2 v[146:147], v[34:35], off offset:2560
	global_load_dwordx2 v[148:149], v[34:35], off offset:3072
	global_load_dwordx2 v[108:109], v[34:35], off offset:3584
	s_nop 0
	s_nop 0
	s_nop 0
	s_nop 0
	s_waitcnt vmcnt(4)
	v_lshlrev_b32_e32 v113, 16, v104
	v_and_b32_e32 v111, 0xffff0000, v104
	v_lshlrev_b32_e32 v118, 16, v105
	v_and_b32_e32 v119, 0xffff0000, v105
	s_waitcnt vmcnt(0)
	v_lshlrev_b32_e32 v107, 16, v108
	v_and_b32_e32 v105, 0xffff0000, v108
	v_lshlrev_b32_e32 v108, 16, v109
	v_and_b32_e32 v109, 0xffff0000, v109
	v_and_b32_e32 v139, 0xffff0000, v115
	v_and_b32_e32 v137, 0xffff0000, v114
	v_lshlrev_b32_e32 v138, 16, v115
	v_mul_f32_e32 v0, v139, v139
	v_lshlrev_b32_e32 v136, 16, v114
	v_pk_fma_f32 v[114:115], v[138:139], v[138:139], v[0:1] op_sel_hi:[1,1,0]
	v_and_b32_e32 v135, 0xffff0000, v117
	v_and_b32_e32 v134, 0xffff0000, v116
	v_mul_f32_e32 v0, v137, v137
	v_lshlrev_b32_e32 v133, 16, v117
	v_lshlrev_b32_e32 v132, 16, v116
	v_pk_mul_f32 v[116:117], v[134:135], v[134:135]
	v_lshlrev_b32_e32 v128, 16, v120
	v_and_b32_e32 v129, 0xffff0000, v120
	v_lshlrev_b32_e32 v130, 16, v121
	v_and_b32_e32 v131, 0xffff0000, v121
	v_pk_fma_f32 v[120:121], v[136:137], v[136:137], v[0:1] op_sel_hi:[1,1,0]
	v_pk_fma_f32 v[116:117], v[132:133], v[132:133], v[116:117]
	v_mov_b32_e32 v112, v120
	v_mov_b32_e32 v124, v114
	v_mov_b32_e32 v125, v113
	v_mul_f32_e32 v104, v111, v111
	v_pk_add_f32 v[114:115], v[120:121], v[114:115]
	v_pk_mul_f32 v[120:121], v[112:113], v[124:125]
	v_pk_add_f32 v[116:117], v[116:117], v[116:117] op_sel:[0,1] op_sel_hi:[1,0]
	v_mov_b32_e32 v115, v121
	v_mov_b32_e32 v117, v104
	v_mul_f32_e32 v0, v129, v129
	v_pk_add_f32 v[114:115], v[114:115], v[116:117]
	v_pk_fma_f32 v[116:117], v[128:129], v[128:129], v[0:1] op_sel_hi:[1,1,0]
	v_mul_f32_e32 v0, v131, v131
	v_mul_f32_e32 v106, v118, v118
	v_mul_f32_e32 v110, v119, v119
	v_pk_fma_f32 v[120:121], v[130:131], v[130:131], v[0:1] op_sel_hi:[1,1,0]
	v_mov_b32_e32 v117, v106
	v_mov_b32_e32 v121, v110
	v_pk_add_f32 v[116:117], v[116:117], v[120:121]
	v_and_b32_e32 v127, 0xffff0000, v123
	v_and_b32_e32 v126, 0xffff0000, v122
	v_pk_add_f32 v[150:151], v[114:115], v[116:117]
	v_lshlrev_b32_e32 v125, 16, v123
	v_lshlrev_b32_e32 v124, 16, v122
	v_pk_mul_f32 v[114:115], v[126:127], v[126:127]
	v_and_b32_e32 v123, 0xffff0000, v147
	v_pk_fma_f32 v[114:115], v[124:125], v[124:125], v[114:115]
	v_and_b32_e32 v122, 0xffff0000, v146
	v_pk_add_f32 v[152:153], v[114:115], v[114:115] op_sel:[0,1] op_sel_hi:[1,0]
	v_lshlrev_b32_e32 v121, 16, v147
	v_lshlrev_b32_e32 v120, 16, v146
	v_pk_mul_f32 v[114:115], v[122:123], v[122:123]
	v_lshlrev_b32_e32 v116, 16, v149
	v_pk_fma_f32 v[146:147], v[120:121], v[120:121], v[114:115]
	v_lshlrev_b32_e32 v114, 16, v148
	v_and_b32_e32 v115, 0xffff0000, v148
	v_and_b32_e32 v117, 0xffff0000, v149
	v_pk_add_f32 v[148:149], v[150:151], v[150:151] op_sel:[0,1] op_sel_hi:[1,0]
	v_mov_b32_e32 v150, v152
	v_mov_b32_e32 v106, v148
	v_mov_b32_e32 v151, v107
	v_mul_f32_e32 v0, v105, v105
	v_pk_add_f32 v[148:149], v[148:149], v[152:153]
	v_pk_mul_f32 v[150:151], v[106:107], v[150:151]
	v_pk_add_f32 v[146:147], v[146:147], v[146:147] op_sel:[0,1] op_sel_hi:[1,0]
	v_mov_b32_e32 v149, v151
	v_mov_b32_e32 v147, v0
	v_mul_f32_e32 v0, v115, v115
	v_pk_add_f32 v[146:147], v[148:149], v[146:147]
	v_pk_fma_f32 v[148:149], v[114:115], v[114:115], v[0:1] op_sel_hi:[1,1,0]
	v_mul_f32_e32 v0, v117, v117
	v_mul_f32_e32 v104, v108, v108
	v_mul_f32_e32 v110, v109, v109
	v_pk_fma_f32 v[150:151], v[116:117], v[116:117], v[0:1] op_sel_hi:[1,1,0]
	v_mov_b32_e32 v149, v104
	v_mov_b32_e32 v151, v110
	v_pk_add_f32 v[148:149], v[148:149], v[150:151]
	v_pk_add_f32 v[94:95], v[214:215], 1.0 op_sel_hi:[1,0]
	v_pk_add_f32 v[146:147], v[146:147], v[148:149]
	v_pk_add_f32 v[96:97], v[216:217], 1.0 op_sel_hi:[1,0]
	v_add_f32_e32 v0, v146, v147
	v_lshl_add_u64 v[146:147], s[10:11], 0, v[100:101]
	v_pk_add_f32 v[88:89], v[208:209], 1.0 op_sel_hi:[1,0]
	v_pk_add_f32 v[86:87], v[206:207], 1.0 op_sel_hi:[1,0]
	v_pk_add_f32 v[80:81], v[200:201], 1.0 op_sel_hi:[1,0]
	s_nop 1
	v_add_f32_dpp v0, v0, v0 quad_perm:[1,0,3,2] row_mask:0xf bank_mask:0xf
	v_pk_add_f32 v[78:79], v[198:199], 1.0 op_sel_hi:[1,0]
	v_mov_b32_e32 v110, v113
	v_pk_add_f32 v[72:73], v[192:193], 1.0 op_sel_hi:[1,0]
	v_pk_add_f32 v[70:71], v[190:191], 1.0 op_sel_hi:[1,0]
	s_nop 1
	v_add_f32_dpp v0, v0, v0 quad_perm:[2,3,0,1] row_mask:0xf bank_mask:0xf
	v_pk_add_f32 v[64:65], v[184:185], 1.0 op_sel_hi:[1,0]
	v_pk_add_f32 v[62:63], v[182:183], 1.0 op_sel_hi:[1,0]
	v_pk_add_f32 v[56:57], v[176:177], 1.0 op_sel_hi:[1,0]
	v_pk_add_f32 v[54:55], v[174:175], 1.0 op_sel_hi:[1,0]
	s_nop 1
	v_add_f32_dpp v0, v0, v0 row_half_mirror row_mask:0xf bank_mask:0xf
	v_pk_add_f32 v[48:49], v[168:169], 1.0 op_sel_hi:[1,0]
	v_pk_add_f32 v[46:47], v[166:167], 1.0 op_sel_hi:[1,0]
	v_readlane_b32 s4, v254, 13
	s_add_i32 s8, s8, s4
	s_nop 1
	v_add_f32_dpp v0, v0, v0 row_mirror row_mask:0xf bank_mask:0xf
	v_pk_add_f32 v[40:41], v[160:161], 1.0 op_sel_hi:[1,0]
	v_pk_add_f32 v[38:39], v[158:159], 1.0 op_sel_hi:[1,0]
	s_add_u32 s10, s10, s86
	s_addc_u32 s11, s11, s87
	v_mov_b32_e32 v104, v0
	s_nop 1
	v_permlane16_swap_b32 v0, v104
	v_add_f32_e32 v0, v0, v104
	s_cmpk_lt_i32 s8, 0x2800
	v_readlane_b32 s5, v254, 14
	v_mov_b32_e32 v104, v0
	s_nop 1
	v_permlane32_swap_b32 v0, v104
	v_add_f32_e32 v0, v0, v104
	v_fmamk_f32 v0, v0, 0x3a000000, v224
	v_rsq_f32_e32 v0, v0
	v_mov_b32_e32 v104, v107
	v_pk_mul_f32 v[136:137], v[0:1], v[136:137] op_sel_hi:[0,1]
	v_pk_mul_f32 v[138:139], v[0:1], v[138:139] op_sel_hi:[0,1]
	v_pk_mul_f32 v[136:137], v[10:11], v[136:137]
	v_pk_mul_f32 v[138:139], v[12:13], v[138:139]
	v_pk_fma_f32 v[90:91], v[94:95], v[136:137], v[210:211]
	v_pk_fma_f32 v[92:93], v[96:97], v[138:139], v[212:213]
	v_cvt_pk_bf16_f32 v94, v90, v91
	v_add_co_u32_e32 v90, vcc, s51, v146
	v_cvt_pk_bf16_f32 v95, v92, v93
	s_nop 0
	v_addc_co_u32_e32 v91, vcc, 0, v147, vcc
	v_mov_b32_e32 v92, v133
	v_mov_b32_e32 v93, v135
	v_mov_b32_e32 v133, v134
	global_store_dwordx2 v[90:91], v[94:95], off
	v_pk_mul_f32 v[92:93], v[0:1], v[92:93] op_sel_hi:[0,1]
	v_pk_mul_f32 v[94:95], v[0:1], v[132:133] op_sel_hi:[0,1]
	v_pk_mul_f32 v[94:95], v[2:3], v[94:95]
	v_pk_mul_f32 v[92:93], v[4:5], v[92:93]
	v_pk_fma_f32 v[82:83], v[86:87], v[94:95], v[202:203]
	v_pk_fma_f32 v[84:85], v[88:89], v[92:93], v[204:205]
	v_cvt_pk_bf16_f32 v82, v82, v83
	v_cvt_pk_bf16_f32 v83, v84, v85
	global_store_dwordx2 v[90:91], v[82:83], off offset:512
	v_pk_mul_f32 v[82:83], v[0:1], v[130:131] op_sel_hi:[0,1]
	v_pk_mul_f32 v[84:85], v[0:1], v[128:129] op_sel_hi:[0,1]
	v_pk_mul_f32 v[84:85], v[6:7], v[84:85]
	v_pk_mul_f32 v[82:83], v[8:9], v[82:83]
	v_pk_fma_f32 v[74:75], v[78:79], v[84:85], v[194:195]
	v_pk_fma_f32 v[76:77], v[80:81], v[82:83], v[196:197]
	v_cvt_pk_bf16_f32 v74, v74, v75
	v_cvt_pk_bf16_f32 v75, v76, v77
	global_store_dwordx2 v[90:91], v[74:75], off offset:1024
	v_pk_mul_f32 v[74:75], v[118:119], v[0:1] op_sel_hi:[1,0]
	v_pk_mul_f32 v[76:77], v[110:111], v[0:1] op_sel_hi:[1,0]
	v_pk_mul_f32 v[74:75], v[16:17], v[74:75]
	v_pk_mul_f32 v[76:77], v[14:15], v[76:77]
	v_pk_fma_f32 v[68:69], v[72:73], v[74:75], v[188:189]
	v_pk_fma_f32 v[66:67], v[70:71], v[76:77], v[186:187]
	s_nop 0
	v_cvt_pk_bf16_f32 v66, v66, v67
	v_cvt_pk_bf16_f32 v67, v68, v69
	global_store_dwordx2 v[90:91], v[66:67], off offset:1536
	v_mov_b32_e32 v66, v125
	v_mov_b32_e32 v67, v127
	v_mov_b32_e32 v125, v126
	v_pk_mul_f32 v[66:67], v[0:1], v[66:67] op_sel_hi:[0,1]
	v_pk_mul_f32 v[68:69], v[0:1], v[124:125] op_sel_hi:[0,1]
	v_pk_mul_f32 v[68:69], v[18:19], v[68:69]
	v_pk_mul_f32 v[66:67], v[20:21], v[66:67]
	v_pk_fma_f32 v[58:59], v[62:63], v[68:69], v[178:179]
	v_pk_fma_f32 v[60:61], v[64:65], v[66:67], v[180:181]
	v_cvt_pk_bf16_f32 v58, v58, v59
	v_cvt_pk_bf16_f32 v59, v60, v61
	global_store_dwordx2 v[90:91], v[58:59], off offset:2048
	v_mov_b32_e32 v58, v121
	v_mov_b32_e32 v59, v123
	v_mov_b32_e32 v121, v122
	v_pk_mul_f32 v[58:59], v[0:1], v[58:59] op_sel_hi:[0,1]
	v_pk_mul_f32 v[60:61], v[0:1], v[120:121] op_sel_hi:[0,1]
	v_pk_mul_f32 v[60:61], v[22:23], v[60:61]
	v_pk_mul_f32 v[58:59], v[24:25], v[58:59]
	v_pk_fma_f32 v[50:51], v[54:55], v[60:61], v[170:171]
	v_pk_fma_f32 v[52:53], v[56:57], v[58:59], v[172:173]
	v_cvt_pk_bf16_f32 v50, v50, v51
	v_cvt_pk_bf16_f32 v51, v52, v53
	global_store_dwordx2 v[90:91], v[50:51], off offset:2560
	v_pk_mul_f32 v[50:51], v[0:1], v[116:117] op_sel_hi:[0,1]
	v_pk_mul_f32 v[52:53], v[0:1], v[114:115] op_sel_hi:[0,1]
	v_pk_mul_f32 v[52:53], v[26:27], v[52:53]
	v_pk_mul_f32 v[50:51], v[28:29], v[50:51]
	v_pk_fma_f32 v[42:43], v[46:47], v[52:53], v[162:163]
	v_pk_fma_f32 v[44:45], v[48:49], v[50:51], v[164:165]
	v_cvt_pk_bf16_f32 v42, v42, v43
	v_cvt_pk_bf16_f32 v43, v44, v45
	global_store_dwordx2 v[90:91], v[42:43], off offset:3072
	v_pk_mul_f32 v[42:43], v[108:109], v[0:1] op_sel_hi:[1,0]
	v_pk_mul_f32 v[44:45], v[104:105], v[0:1] op_sel_hi:[1,0]
	v_pk_mul_f32 v[42:43], v[32:33], v[42:43]
	v_pk_mul_f32 v[44:45], v[30:31], v[44:45]
	v_pk_fma_f32 v[36:37], v[40:41], v[42:43], v[156:157]
	v_pk_fma_f32 v[34:35], v[38:39], v[44:45], v[154:155]
	s_nop 0
	v_cvt_pk_bf16_f32 v34, v34, v35
	v_cvt_pk_bf16_f32 v35, v36, v37
	global_store_dwordx2 v[90:91], v[34:35], off offset:3584
	s_cbranch_scc0 .Lnh1_exit
	s_cmpk_gt_i32 s8, 0x1fff
	s_cbranch_scc1 .LBB0_992
	s_branch .Lnh1_B
.Lnh1_exit:
.LBB0_993:
	s_waitcnt vmcnt(0)
	s_barrier
	v_mbcnt_lo_u32_b32 v0, -1, 0
	v_mbcnt_hi_u32_b32 v0, -1, v0
	s_nop 0
	v_sub_u32_e32 v0, 0, v0
	v_cmp_eq_u32_e32 vcc, s81, v0
	s_and_saveexec_b64 s[4:5], vcc
	s_cbranch_execz .LBB0_1037
	v_readlane_b32 s6, v252, 13
	v_readlane_b32 s8, v254, 9
	v_readlane_b32 s7, v252, 14
	v_readlane_b32 s42, v252, 15
	v_mov_b32_e32 v0, s8
	s_waitcnt vmcnt(0) expcnt(0) lgkmcnt(0)
	ds_read_b32 v2, v0
	v_readlane_b32 s8, v254, 10
	s_waitcnt lgkmcnt(0)
	v_cmp_ne_u32_e32 vcc, 0, v2
	v_mov_b32_e32 v0, s8
	ds_read_b32 v0, v0
	s_cbranch_vccnz .LBB0_1008
	v_readlane_b32 s8, v252, 10
	v_readlane_b32 s9, v252, 11
	s_load_dwordx2 s[12:13], s[8:9], 0x4
	s_add_u32 s8, s6, 0x1000
	s_addc_u32 s9, s7, 0
	s_add_u32 s10, s6, 0x1100
	s_addc_u32 s11, s7, 0
	s_waitcnt lgkmcnt(0)
	s_mul_i32 s36, s12, s3
	s_add_u32 s12, s6, 0x1200
	s_mul_i32 s36, s36, s13
	s_addc_u32 s13, s7, 0
	s_add_u32 s14, s6, 0x1300
	s_addc_u32 s15, s7, 0
	s_mov_b32 s37, 1
	s_mov_b64 s[16:17], 0
	s_branch .LBB0_998

.LBB0_1600:
	s_add_i32 s5, s4, 0xffffe000
	s_ashr_i32 s5, s5, 10
	s_add_i32 s5, s5, 1
	s_cmpk_gt_i32 s4, 0x1fff
	v_lshl_add_u64 v[34:35], s[8:9], 0, v[102:103]
	s_cselect_b32 s5, s5, 0
	v_add_co_u32_e32 v34, vcc, 0x27a00000, v34
	v_mad_i64_i32 v[36:37], s[6:7], s5, v245, v[98:99]
	s_nop 0
	v_addc_co_u32_e32 v35, vcc, 0, v35, vcc
	v_add_co_u32_e32 v70, vcc, 0x2000, v36
	s_nop 1
	v_addc_co_u32_e32 v71, vcc, 0, v37, vcc
	global_load_dwordx4 v[210:213], v[36:37], off
	global_load_dwordx4 v[202:205], v[36:37], off offset:1024
	global_load_dwordx4 v[214:217], v[70:71], off
	global_load_dwordx4 v[206:209], v[70:71], off offset:1024
	global_load_dwordx2 v[114:115], v[34:35], off
	global_load_dwordx2 v[116:117], v[34:35], off offset:512
	global_load_dwordx2 v[120:121], v[34:35], off offset:1024
	global_load_dwordx2 v[104:105], v[34:35], off offset:1536
	global_load_dwordx4 v[194:197], v[36:37], off offset:2048
	global_load_dwordx4 v[186:189], v[36:37], off offset:3072
	v_add_co_u32_e32 v38, vcc, s97, v36
	s_nop 1
	v_addc_co_u32_e32 v39, vcc, 0, v37, vcc
	v_add_co_u32_e32 v40, vcc, s91, v36
	s_nop 1
	v_addc_co_u32_e32 v41, vcc, 0, v37, vcc
	global_load_dwordx4 v[178:181], v[38:39], off
	global_load_dwordx4 v[170:173], v[38:39], off offset:1024
	global_load_dwordx4 v[182:185], v[40:41], off
	global_load_dwordx4 v[174:177], v[40:41], off offset:1024
	global_load_dwordx2 v[122:123], v[34:35], off offset:2048
	global_load_dwordx2 v[146:147], v[34:35], off offset:2560
	global_load_dwordx2 v[148:149], v[34:35], off offset:3072
	global_load_dwordx2 v[108:109], v[34:35], off offset:3584
	global_load_dwordx4 v[162:165], v[38:39], off offset:2048
	s_nop 0
	global_load_dwordx4 v[154:157], v[38:39], off offset:3072
	global_load_dwordx4 v[166:169], v[40:41], off offset:2048
	s_nop 0
	global_load_dwordx4 v[158:161], v[40:41], off offset:3072
	s_nop 0
	global_load_dwordx4 v[198:201], v[70:71], off offset:2048
	s_nop 0
	global_load_dwordx4 v[190:193], v[70:71], off offset:3072
	s_waitcnt vmcnt(14)
	v_lshlrev_b32_e32 v113, 16, v104
	v_and_b32_e32 v111, 0xffff0000, v104
	v_lshlrev_b32_e32 v118, 16, v105
	v_and_b32_e32 v119, 0xffff0000, v105
	s_waitcnt vmcnt(6)
	v_lshlrev_b32_e32 v107, 16, v108
	v_and_b32_e32 v105, 0xffff0000, v108
	v_lshlrev_b32_e32 v108, 16, v109
	v_and_b32_e32 v109, 0xffff0000, v109
	v_and_b32_e32 v139, 0xffff0000, v115
	v_and_b32_e32 v137, 0xffff0000, v114
	v_lshlrev_b32_e32 v138, 16, v115
	v_mul_f32_e32 v0, v139, v139
	v_lshlrev_b32_e32 v136, 16, v114
	v_pk_fma_f32 v[114:115], v[138:139], v[138:139], v[0:1] op_sel_hi:[1,1,0]
	v_and_b32_e32 v135, 0xffff0000, v117
	v_and_b32_e32 v134, 0xffff0000, v116
	v_mul_f32_e32 v0, v137, v137
	v_lshlrev_b32_e32 v133, 16, v117
	v_lshlrev_b32_e32 v132, 16, v116
	v_pk_mul_f32 v[116:117], v[134:135], v[134:135]
	v_lshlrev_b32_e32 v128, 16, v120
	v_and_b32_e32 v129, 0xffff0000, v120
	v_lshlrev_b32_e32 v130, 16, v121
	v_and_b32_e32 v131, 0xffff0000, v121
	v_pk_fma_f32 v[120:121], v[136:137], v[136:137], v[0:1] op_sel_hi:[1,1,0]
	v_pk_fma_f32 v[116:117], v[132:133], v[132:133], v[116:117]
	v_mov_b32_e32 v112, v120
	v_mov_b32_e32 v124, v114
	v_mov_b32_e32 v125, v113
	v_mul_f32_e32 v104, v111, v111
	v_pk_add_f32 v[114:115], v[120:121], v[114:115]
	v_pk_mul_f32 v[120:121], v[112:113], v[124:125]
	v_pk_add_f32 v[116:117], v[116:117], v[116:117] op_sel:[0,1] op_sel_hi:[1,0]
	v_mov_b32_e32 v115, v121
	v_mov_b32_e32 v117, v104
	v_mul_f32_e32 v0, v129, v129
	v_pk_add_f32 v[114:115], v[114:115], v[116:117]
	v_pk_fma_f32 v[116:117], v[128:129], v[128:129], v[0:1] op_sel_hi:[1,1,0]
	v_mul_f32_e32 v0, v131, v131
	v_mul_f32_e32 v106, v118, v118
	v_mul_f32_e32 v110, v119, v119
	v_pk_fma_f32 v[120:121], v[130:131], v[130:131], v[0:1] op_sel_hi:[1,1,0]
	v_mov_b32_e32 v117, v106
	v_mov_b32_e32 v121, v110
	v_pk_add_f32 v[116:117], v[116:117], v[120:121]
	v_and_b32_e32 v127, 0xffff0000, v123
	v_and_b32_e32 v126, 0xffff0000, v122
	v_pk_add_f32 v[150:151], v[114:115], v[116:117]
	v_lshlrev_b32_e32 v125, 16, v123
	v_lshlrev_b32_e32 v124, 16, v122
	v_pk_mul_f32 v[114:115], v[126:127], v[126:127]
	v_and_b32_e32 v123, 0xffff0000, v147
	v_pk_fma_f32 v[114:115], v[124:125], v[124:125], v[114:115]
	v_and_b32_e32 v122, 0xffff0000, v146
	v_pk_add_f32 v[152:153], v[114:115], v[114:115] op_sel:[0,1] op_sel_hi:[1,0]
	v_lshlrev_b32_e32 v121, 16, v147
	v_lshlrev_b32_e32 v120, 16, v146
	v_pk_mul_f32 v[114:115], v[122:123], v[122:123]
	v_lshlrev_b32_e32 v116, 16, v149
	v_pk_fma_f32 v[146:147], v[120:121], v[120:121], v[114:115]
	v_lshlrev_b32_e32 v114, 16, v148
	v_and_b32_e32 v115, 0xffff0000, v148
	v_and_b32_e32 v117, 0xffff0000, v149
	v_pk_add_f32 v[148:149], v[150:151], v[150:151] op_sel:[0,1] op_sel_hi:[1,0]
	v_mov_b32_e32 v150, v152
	v_mov_b32_e32 v106, v148
	v_mov_b32_e32 v151, v107
	v_mul_f32_e32 v0, v105, v105
	v_pk_add_f32 v[148:149], v[148:149], v[152:153]
	v_pk_mul_f32 v[150:151], v[106:107], v[150:151]
	v_pk_add_f32 v[146:147], v[146:147], v[146:147] op_sel:[0,1] op_sel_hi:[1,0]
	v_mov_b32_e32 v149, v151
	v_mov_b32_e32 v147, v0
	v_mul_f32_e32 v0, v115, v115
	v_pk_add_f32 v[146:147], v[148:149], v[146:147]
	v_pk_fma_f32 v[148:149], v[114:115], v[114:115], v[0:1] op_sel_hi:[1,1,0]
	v_mul_f32_e32 v0, v117, v117
	v_mul_f32_e32 v104, v108, v108
	v_mul_f32_e32 v110, v109, v109
	v_pk_fma_f32 v[150:151], v[116:117], v[116:117], v[0:1] op_sel_hi:[1,1,0]
	v_mov_b32_e32 v149, v104
	v_mov_b32_e32 v151, v110
	v_pk_add_f32 v[148:149], v[148:149], v[150:151]
	v_pk_add_f32 v[94:95], v[214:215], 1.0 op_sel_hi:[1,0]
	v_pk_add_f32 v[146:147], v[146:147], v[148:149]
	v_pk_add_f32 v[96:97], v[216:217], 1.0 op_sel_hi:[1,0]
	v_add_f32_e32 v0, v146, v147
	v_lshl_add_u64 v[146:147], s[8:9], 0, v[100:101]
	v_pk_add_f32 v[88:89], v[208:209], 1.0 op_sel_hi:[1,0]
	v_pk_add_f32 v[86:87], v[206:207], 1.0 op_sel_hi:[1,0]
	s_waitcnt vmcnt(1)
	v_pk_add_f32 v[80:81], v[200:201], 1.0 op_sel_hi:[1,0]
	s_nop 1
	v_add_f32_dpp v0, v0, v0 quad_perm:[1,0,3,2] row_mask:0xf bank_mask:0xf
	v_pk_add_f32 v[78:79], v[198:199], 1.0 op_sel_hi:[1,0]
	v_mov_b32_e32 v110, v113
	s_waitcnt vmcnt(0)
	v_pk_add_f32 v[72:73], v[192:193], 1.0 op_sel_hi:[1,0]
	v_pk_add_f32 v[70:71], v[190:191], 1.0 op_sel_hi:[1,0]
	s_nop 1
	v_add_f32_dpp v0, v0, v0 quad_perm:[2,3,0,1] row_mask:0xf bank_mask:0xf
	v_pk_add_f32 v[64:65], v[184:185], 1.0 op_sel_hi:[1,0]
	v_pk_add_f32 v[62:63], v[182:183], 1.0 op_sel_hi:[1,0]
	v_pk_add_f32 v[56:57], v[176:177], 1.0 op_sel_hi:[1,0]
	v_pk_add_f32 v[54:55], v[174:175], 1.0 op_sel_hi:[1,0]
	s_nop 1
	v_add_f32_dpp v0, v0, v0 row_half_mirror row_mask:0xf bank_mask:0xf
	v_pk_add_f32 v[48:49], v[168:169], 1.0 op_sel_hi:[1,0]
	v_pk_add_f32 v[46:47], v[166:167], 1.0 op_sel_hi:[1,0]
	v_readlane_b32 s6, v254, 13
	s_add_i32 s4, s4, s6
	s_nop 1
	v_add_f32_dpp v0, v0, v0 row_mirror row_mask:0xf bank_mask:0xf
	v_pk_add_f32 v[40:41], v[160:161], 1.0 op_sel_hi:[1,0]
	v_pk_add_f32 v[38:39], v[158:159], 1.0 op_sel_hi:[1,0]
	s_add_u32 s8, s8, s86
	s_addc_u32 s9, s9, s87
	v_mov_b32_e32 v104, v0
	s_nop 1
	v_permlane16_swap_b32 v0, v104
	v_add_f32_e32 v0, v0, v104
	s_cmpk_lt_i32 s4, 0x2800
	v_readlane_b32 s7, v254, 14
	v_mov_b32_e32 v104, v0
	s_nop 1
	v_permlane32_swap_b32 v0, v104
	v_add_f32_e32 v0, v0, v104
	v_fmamk_f32 v0, v0, 0x3a000000, v224
	v_rsq_f32_e32 v0, v0
	v_mov_b32_e32 v104, v107
	v_pk_mul_f32 v[136:137], v[0:1], v[136:137] op_sel_hi:[0,1]
	v_pk_mul_f32 v[138:139], v[0:1], v[138:139] op_sel_hi:[0,1]
	v_pk_mul_f32 v[136:137], v[10:11], v[136:137]
	v_pk_mul_f32 v[138:139], v[12:13], v[138:139]
	v_pk_fma_f32 v[90:91], v[94:95], v[136:137], v[210:211]
	v_pk_fma_f32 v[92:93], v[96:97], v[138:139], v[212:213]
	v_cvt_pk_bf16_f32 v94, v90, v91
	v_add_co_u32_e32 v90, vcc, s51, v146
	v_cvt_pk_bf16_f32 v95, v92, v93
	s_nop 0
	v_addc_co_u32_e32 v91, vcc, 0, v147, vcc
	v_mov_b32_e32 v92, v133
	v_mov_b32_e32 v93, v135
	v_mov_b32_e32 v133, v134
	global_store_dwordx2 v[90:91], v[94:95], off
	v_pk_mul_f32 v[92:93], v[0:1], v[92:93] op_sel_hi:[0,1]
	v_pk_mul_f32 v[94:95], v[0:1], v[132:133] op_sel_hi:[0,1]
	v_pk_mul_f32 v[94:95], v[2:3], v[94:95]
	v_pk_mul_f32 v[92:93], v[4:5], v[92:93]
	v_pk_fma_f32 v[82:83], v[86:87], v[94:95], v[202:203]
	v_pk_fma_f32 v[84:85], v[88:89], v[92:93], v[204:205]
	v_cvt_pk_bf16_f32 v82, v82, v83
	v_cvt_pk_bf16_f32 v83, v84, v85
	global_store_dwordx2 v[90:91], v[82:83], off offset:512
	v_pk_mul_f32 v[82:83], v[0:1], v[130:131] op_sel_hi:[0,1]
	v_pk_mul_f32 v[84:85], v[0:1], v[128:129] op_sel_hi:[0,1]
	v_pk_mul_f32 v[84:85], v[6:7], v[84:85]
	v_pk_mul_f32 v[82:83], v[8:9], v[82:83]
	v_pk_fma_f32 v[74:75], v[78:79], v[84:85], v[194:195]
	v_pk_fma_f32 v[76:77], v[80:81], v[82:83], v[196:197]
	v_cvt_pk_bf16_f32 v74, v74, v75
	v_cvt_pk_bf16_f32 v75, v76, v77
	global_store_dwordx2 v[90:91], v[74:75], off offset:1024
	v_pk_mul_f32 v[74:75], v[118:119], v[0:1] op_sel_hi:[1,0]
	v_pk_mul_f32 v[76:77], v[110:111], v[0:1] op_sel_hi:[1,0]
	v_pk_mul_f32 v[74:75], v[16:17], v[74:75]
	v_pk_mul_f32 v[76:77], v[14:15], v[76:77]
	v_pk_fma_f32 v[68:69], v[72:73], v[74:75], v[188:189]
	v_pk_fma_f32 v[66:67], v[70:71], v[76:77], v[186:187]
	s_nop 0
	v_cvt_pk_bf16_f32 v66, v66, v67
	v_cvt_pk_bf16_f32 v67, v68, v69
	global_store_dwordx2 v[90:91], v[66:67], off offset:1536
	v_mov_b32_e32 v66, v125
	v_mov_b32_e32 v67, v127
	v_mov_b32_e32 v125, v126
	v_pk_mul_f32 v[66:67], v[0:1], v[66:67] op_sel_hi:[0,1]
	v_pk_mul_f32 v[68:69], v[0:1], v[124:125] op_sel_hi:[0,1]
	v_pk_mul_f32 v[68:69], v[18:19], v[68:69]
	v_pk_mul_f32 v[66:67], v[20:21], v[66:67]
	v_pk_fma_f32 v[58:59], v[62:63], v[68:69], v[178:179]
	v_pk_fma_f32 v[60:61], v[64:65], v[66:67], v[180:181]
	v_cvt_pk_bf16_f32 v58, v58, v59
	v_cvt_pk_bf16_f32 v59, v60, v61
	global_store_dwordx2 v[90:91], v[58:59], off offset:2048
	v_mov_b32_e32 v58, v121
	v_mov_b32_e32 v59, v123
	v_mov_b32_e32 v121, v122
	v_pk_mul_f32 v[58:59], v[0:1], v[58:59] op_sel_hi:[0,1]
	v_pk_mul_f32 v[60:61], v[0:1], v[120:121] op_sel_hi:[0,1]
	v_pk_mul_f32 v[60:61], v[22:23], v[60:61]
	v_pk_mul_f32 v[58:59], v[24:25], v[58:59]
	v_pk_fma_f32 v[50:51], v[54:55], v[60:61], v[170:171]
	v_pk_fma_f32 v[52:53], v[56:57], v[58:59], v[172:173]
	v_cvt_pk_bf16_f32 v50, v50, v51
	v_cvt_pk_bf16_f32 v51, v52, v53
	global_store_dwordx2 v[90:91], v[50:51], off offset:2560
	v_pk_mul_f32 v[50:51], v[0:1], v[116:117] op_sel_hi:[0,1]
	v_pk_mul_f32 v[52:53], v[0:1], v[114:115] op_sel_hi:[0,1]
	v_pk_mul_f32 v[52:53], v[26:27], v[52:53]
	v_pk_mul_f32 v[50:51], v[28:29], v[50:51]
	v_pk_fma_f32 v[42:43], v[46:47], v[52:53], v[162:163]
	v_pk_fma_f32 v[44:45], v[48:49], v[50:51], v[164:165]
	v_cvt_pk_bf16_f32 v42, v42, v43
	v_cvt_pk_bf16_f32 v43, v44, v45
	global_store_dwordx2 v[90:91], v[42:43], off offset:3072
	v_pk_mul_f32 v[42:43], v[108:109], v[0:1] op_sel_hi:[1,0]
	v_pk_mul_f32 v[44:45], v[104:105], v[0:1] op_sel_hi:[1,0]
	v_pk_mul_f32 v[42:43], v[32:33], v[42:43]
	v_pk_mul_f32 v[44:45], v[30:31], v[44:45]
	v_pk_fma_f32 v[36:37], v[40:41], v[42:43], v[156:157]
	v_pk_fma_f32 v[34:35], v[38:39], v[44:45], v[154:155]
	s_nop 0
	v_cvt_pk_bf16_f32 v34, v34, v35
	v_cvt_pk_bf16_f32 v35, v36, v37
	global_store_dwordx2 v[90:91], v[34:35], off offset:3584
	s_cbranch_scc0 .Lnh2_exit
	s_cmpk_gt_i32 s4, 0x1fff
	s_cbranch_scc1 .LBB0_1600
.Lnh2_B:
	s_add_i32 s5, s4, 0xffffe000
	s_ashr_i32 s5, s5, 10
	s_add_i32 s5, s5, 1
	s_cmpk_gt_i32 s4, 0x1fff
	v_lshl_add_u64 v[34:35], s[8:9], 0, v[102:103]
	s_cselect_b32 s5, s5, 0
	v_add_co_u32_e32 v34, vcc, 0x27a00000, v34
	v_mad_i64_i32 v[36:37], s[6:7], s5, v245, v[98:99]
	s_nop 0
	v_addc_co_u32_e32 v35, vcc, 0, v35, vcc
	v_add_co_u32_e32 v70, vcc, 0x2000, v36
	s_nop 1
	v_addc_co_u32_e32 v71, vcc, 0, v37, vcc
	global_load_dwordx2 v[114:115], v[34:35], off
	global_load_dwordx2 v[116:117], v[34:35], off offset:512
	global_load_dwordx2 v[120:121], v[34:35], off offset:1024
	global_load_dwordx2 v[104:105], v[34:35], off offset:1536
	v_add_co_u32_e32 v38, vcc, s97, v36
	s_nop 1
	v_addc_co_u32_e32 v39, vcc, 0, v37, vcc
	v_add_co_u32_e32 v40, vcc, s91, v36
	s_nop 1
	v_addc_co_u32_e32 v41, vcc, 0, v37, vcc
	global_load_dwordx2 v[122:123], v[34:35], off offset:2048
	global_load_dwordx2 v[146:147], v[34:35], off offset:2560
	global_load_dwordx2 v[148:149], v[34:35], off offset:3072
	global_load_dwordx2 v[108:109], v[34:35], off offset:3584
	s_nop 0
	s_nop 0
	s_nop 0
	s_nop 0
	s_waitcnt vmcnt(4)
	v_lshlrev_b32_e32 v113, 16, v104
	v_and_b32_e32 v111, 0xffff0000, v104
	v_lshlrev_b32_e32 v118, 16, v105
	v_and_b32_e32 v119, 0xffff0000, v105
	s_waitcnt vmcnt(0)
	v_lshlrev_b32_e32 v107, 16, v108
	v_and_b32_e32 v105, 0xffff0000, v108
	v_lshlrev_b32_e32 v108, 16, v109
	v_and_b32_e32 v109, 0xffff0000, v109
	v_and_b32_e32 v139, 0xffff0000, v115
	v_and_b32_e32 v137, 0xffff0000, v114
	v_lshlrev_b32_e32 v138, 16, v115
	v_mul_f32_e32 v0, v139, v139
	v_lshlrev_b32_e32 v136, 16, v114
	v_pk_fma_f32 v[114:115], v[138:139], v[138:139], v[0:1] op_sel_hi:[1,1,0]
	v_and_b32_e32 v135, 0xffff0000, v117
	v_and_b32_e32 v134, 0xffff0000, v116
	v_mul_f32_e32 v0, v137, v137
	v_lshlrev_b32_e32 v133, 16, v117
	v_lshlrev_b32_e32 v132, 16, v116
	v_pk_mul_f32 v[116:117], v[134:135], v[134:135]
	v_lshlrev_b32_e32 v128, 16, v120
	v_and_b32_e32 v129, 0xffff0000, v120
	v_lshlrev_b32_e32 v130, 16, v121
	v_and_b32_e32 v131, 0xffff0000, v121
	v_pk_fma_f32 v[120:121], v[136:137], v[136:137], v[0:1] op_sel_hi:[1,1,0]
	v_pk_fma_f32 v[116:117], v[132:133], v[132:133], v[116:117]
	v_mov_b32_e32 v112, v120
	v_mov_b32_e32 v124, v114
	v_mov_b32_e32 v125, v113
	v_mul_f32_e32 v104, v111, v111
	v_pk_add_f32 v[114:115], v[120:121], v[114:115]
	v_pk_mul_f32 v[120:121], v[112:113], v[124:125]
	v_pk_add_f32 v[116:117], v[116:117], v[116:117] op_sel:[0,1] op_sel_hi:[1,0]
	v_mov_b32_e32 v115, v121
	v_mov_b32_e32 v117, v104
	v_mul_f32_e32 v0, v129, v129
	v_pk_add_f32 v[114:115], v[114:115], v[116:117]
	v_pk_fma_f32 v[116:117], v[128:129], v[128:129], v[0:1] op_sel_hi:[1,1,0]
	v_mul_f32_e32 v0, v131, v131
	v_mul_f32_e32 v106, v118, v118
	v_mul_f32_e32 v110, v119, v119
	v_pk_fma_f32 v[120:121], v[130:131], v[130:131], v[0:1] op_sel_hi:[1,1,0]
	v_mov_b32_e32 v117, v106
	v_mov_b32_e32 v121, v110
	v_pk_add_f32 v[116:117], v[116:117], v[120:121]
	v_and_b32_e32 v127, 0xffff0000, v123
	v_and_b32_e32 v126, 0xffff0000, v122
	v_pk_add_f32 v[150:151], v[114:115], v[116:117]
	v_lshlrev_b32_e32 v125, 16, v123
	v_lshlrev_b32_e32 v124, 16, v122
	v_pk_mul_f32 v[114:115], v[126:127], v[126:127]
	v_and_b32_e32 v123, 0xffff0000, v147
	v_pk_fma_f32 v[114:115], v[124:125], v[124:125], v[114:115]
	v_and_b32_e32 v122, 0xffff0000, v146
	v_pk_add_f32 v[152:153], v[114:115], v[114:115] op_sel:[0,1] op_sel_hi:[1,0]
	v_lshlrev_b32_e32 v121, 16, v147
	v_lshlrev_b32_e32 v120, 16, v146
	v_pk_mul_f32 v[114:115], v[122:123], v[122:123]
	v_lshlrev_b32_e32 v116, 16, v149
	v_pk_fma_f32 v[146:147], v[120:121], v[120:121], v[114:115]
	v_lshlrev_b32_e32 v114, 16, v148
	v_and_b32_e32 v115, 0xffff0000, v148
	v_and_b32_e32 v117, 0xffff0000, v149
	v_pk_add_f32 v[148:149], v[150:151], v[150:151] op_sel:[0,1] op_sel_hi:[1,0]
	v_mov_b32_e32 v150, v152
	v_mov_b32_e32 v106, v148
	v_mov_b32_e32 v151, v107
	v_mul_f32_e32 v0, v105, v105
	v_pk_add_f32 v[148:149], v[148:149], v[152:153]
	v_pk_mul_f32 v[150:151], v[106:107], v[150:151]
	v_pk_add_f32 v[146:147], v[146:147], v[146:147] op_sel:[0,1] op_sel_hi:[1,0]
	v_mov_b32_e32 v149, v151
	v_mov_b32_e32 v147, v0
	v_mul_f32_e32 v0, v115, v115
	v_pk_add_f32 v[146:147], v[148:149], v[146:147]
	v_pk_fma_f32 v[148:149], v[114:115], v[114:115], v[0:1] op_sel_hi:[1,1,0]
	v_mul_f32_e32 v0, v117, v117
	v_mul_f32_e32 v104, v108, v108
	v_mul_f32_e32 v110, v109, v109
	v_pk_fma_f32 v[150:151], v[116:117], v[116:117], v[0:1] op_sel_hi:[1,1,0]
	v_mov_b32_e32 v149, v104
	v_mov_b32_e32 v151, v110
	v_pk_add_f32 v[148:149], v[148:149], v[150:151]
	v_pk_add_f32 v[94:95], v[214:215], 1.0 op_sel_hi:[1,0]
	v_pk_add_f32 v[146:147], v[146:147], v[148:149]
	v_pk_add_f32 v[96:97], v[216:217], 1.0 op_sel_hi:[1,0]
	v_add_f32_e32 v0, v146, v147
	v_lshl_add_u64 v[146:147], s[8:9], 0, v[100:101]
	v_pk_add_f32 v[88:89], v[208:209], 1.0 op_sel_hi:[1,0]
	v_pk_add_f32 v[86:87], v[206:207], 1.0 op_sel_hi:[1,0]
	v_pk_add_f32 v[80:81], v[200:201], 1.0 op_sel_hi:[1,0]
	s_nop 1
	v_add_f32_dpp v0, v0, v0 quad_perm:[1,0,3,2] row_mask:0xf bank_mask:0xf
	v_pk_add_f32 v[78:79], v[198:199], 1.0 op_sel_hi:[1,0]
	v_mov_b32_e32 v110, v113
	v_pk_add_f32 v[72:73], v[192:193], 1.0 op_sel_hi:[1,0]
	v_pk_add_f32 v[70:71], v[190:191], 1.0 op_sel_hi:[1,0]
	s_nop 1
	v_add_f32_dpp v0, v0, v0 quad_perm:[2,3,0,1] row_mask:0xf bank_mask:0xf
	v_pk_add_f32 v[64:65], v[184:185], 1.0 op_sel_hi:[1,0]
	v_pk_add_f32 v[62:63], v[182:183], 1.0 op_sel_hi:[1,0]
	v_pk_add_f32 v[56:57], v[176:177], 1.0 op_sel_hi:[1,0]
	v_pk_add_f32 v[54:55], v[174:175], 1.0 op_sel_hi:[1,0]
	s_nop 1
	v_add_f32_dpp v0, v0, v0 row_half_mirror row_mask:0xf bank_mask:0xf
	v_pk_add_f32 v[48:49], v[168:169], 1.0 op_sel_hi:[1,0]
	v_pk_add_f32 v[46:47], v[166:167], 1.0 op_sel_hi:[1,0]
	v_readlane_b32 s6, v254, 13
	s_add_i32 s4, s4, s6
	s_nop 1
	v_add_f32_dpp v0, v0, v0 row_mirror row_mask:0xf bank_mask:0xf
	v_pk_add_f32 v[40:41], v[160:161], 1.0 op_sel_hi:[1,0]
	v_pk_add_f32 v[38:39], v[158:159], 1.0 op_sel_hi:[1,0]
	s_add_u32 s8, s8, s86
	s_addc_u32 s9, s9, s87
	v_mov_b32_e32 v104, v0
	s_nop 1
	v_permlane16_swap_b32 v0, v104
	v_add_f32_e32 v0, v0, v104
	s_cmpk_lt_i32 s4, 0x2800
	v_readlane_b32 s7, v254, 14
	v_mov_b32_e32 v104, v0
	s_nop 1
	v_permlane32_swap_b32 v0, v104
	v_add_f32_e32 v0, v0, v104
	v_fmamk_f32 v0, v0, 0x3a000000, v224
	v_rsq_f32_e32 v0, v0
	v_mov_b32_e32 v104, v107
	v_pk_mul_f32 v[136:137], v[0:1], v[136:137] op_sel_hi:[0,1]
	v_pk_mul_f32 v[138:139], v[0:1], v[138:139] op_sel_hi:[0,1]
	v_pk_mul_f32 v[136:137], v[10:11], v[136:137]
	v_pk_mul_f32 v[138:139], v[12:13], v[138:139]
	v_pk_fma_f32 v[90:91], v[94:95], v[136:137], v[210:211]
	v_pk_fma_f32 v[92:93], v[96:97], v[138:139], v[212:213]
	v_cvt_pk_bf16_f32 v94, v90, v91
	v_add_co_u32_e32 v90, vcc, s51, v146
	v_cvt_pk_bf16_f32 v95, v92, v93
	s_nop 0
	v_addc_co_u32_e32 v91, vcc, 0, v147, vcc
	v_mov_b32_e32 v92, v133
	v_mov_b32_e32 v93, v135
	v_mov_b32_e32 v133, v134
	global_store_dwordx2 v[90:91], v[94:95], off
	v_pk_mul_f32 v[92:93], v[0:1], v[92:93] op_sel_hi:[0,1]
	v_pk_mul_f32 v[94:95], v[0:1], v[132:133] op_sel_hi:[0,1]
	v_pk_mul_f32 v[94:95], v[2:3], v[94:95]
	v_pk_mul_f32 v[92:93], v[4:5], v[92:93]
	v_pk_fma_f32 v[82:83], v[86:87], v[94:95], v[202:203]
	v_pk_fma_f32 v[84:85], v[88:89], v[92:93], v[204:205]
	v_cvt_pk_bf16_f32 v82, v82, v83
	v_cvt_pk_bf16_f32 v83, v84, v85
	global_store_dwordx2 v[90:91], v[82:83], off offset:512
	v_pk_mul_f32 v[82:83], v[0:1], v[130:131] op_sel_hi:[0,1]
	v_pk_mul_f32 v[84:85], v[0:1], v[128:129] op_sel_hi:[0,1]
	v_pk_mul_f32 v[84:85], v[6:7], v[84:85]
	v_pk_mul_f32 v[82:83], v[8:9], v[82:83]
	v_pk_fma_f32 v[74:75], v[78:79], v[84:85], v[194:195]
	v_pk_fma_f32 v[76:77], v[80:81], v[82:83], v[196:197]
	v_cvt_pk_bf16_f32 v74, v74, v75
	v_cvt_pk_bf16_f32 v75, v76, v77
	global_store_dwordx2 v[90:91], v[74:75], off offset:1024
	v_pk_mul_f32 v[74:75], v[118:119], v[0:1] op_sel_hi:[1,0]
	v_pk_mul_f32 v[76:77], v[110:111], v[0:1] op_sel_hi:[1,0]
	v_pk_mul_f32 v[74:75], v[16:17], v[74:75]
	v_pk_mul_f32 v[76:77], v[14:15], v[76:77]
	v_pk_fma_f32 v[68:69], v[72:73], v[74:75], v[188:189]
	v_pk_fma_f32 v[66:67], v[70:71], v[76:77], v[186:187]
	s_nop 0
	v_cvt_pk_bf16_f32 v66, v66, v67
	v_cvt_pk_bf16_f32 v67, v68, v69
	global_store_dwordx2 v[90:91], v[66:67], off offset:1536
	v_mov_b32_e32 v66, v125
	v_mov_b32_e32 v67, v127
	v_mov_b32_e32 v125, v126
	v_pk_mul_f32 v[66:67], v[0:1], v[66:67] op_sel_hi:[0,1]
	v_pk_mul_f32 v[68:69], v[0:1], v[124:125] op_sel_hi:[0,1]
	v_pk_mul_f32 v[68:69], v[18:19], v[68:69]
	v_pk_mul_f32 v[66:67], v[20:21], v[66:67]
	v_pk_fma_f32 v[58:59], v[62:63], v[68:69], v[178:179]
	v_pk_fma_f32 v[60:61], v[64:65], v[66:67], v[180:181]
	v_cvt_pk_bf16_f32 v58, v58, v59
	v_cvt_pk_bf16_f32 v59, v60, v61
	global_store_dwordx2 v[90:91], v[58:59], off offset:2048
	v_mov_b32_e32 v58, v121
	v_mov_b32_e32 v59, v123
	v_mov_b32_e32 v121, v122
	v_pk_mul_f32 v[58:59], v[0:1], v[58:59] op_sel_hi:[0,1]
	v_pk_mul_f32 v[60:61], v[0:1], v[120:121] op_sel_hi:[0,1]
	v_pk_mul_f32 v[60:61], v[22:23], v[60:61]
	v_pk_mul_f32 v[58:59], v[24:25], v[58:59]
	v_pk_fma_f32 v[50:51], v[54:55], v[60:61], v[170:171]
	v_pk_fma_f32 v[52:53], v[56:57], v[58:59], v[172:173]
	v_cvt_pk_bf16_f32 v50, v50, v51
	v_cvt_pk_bf16_f32 v51, v52, v53
	global_store_dwordx2 v[90:91], v[50:51], off offset:2560
	v_pk_mul_f32 v[50:51], v[0:1], v[116:117] op_sel_hi:[0,1]
	v_pk_mul_f32 v[52:53], v[0:1], v[114:115] op_sel_hi:[0,1]
	v_pk_mul_f32 v[52:53], v[26:27], v[52:53]
	v_pk_mul_f32 v[50:51], v[28:29], v[50:51]
	v_pk_fma_f32 v[42:43], v[46:47], v[52:53], v[162:163]
	v_pk_fma_f32 v[44:45], v[48:49], v[50:51], v[164:165]
	v_cvt_pk_bf16_f32 v42, v42, v43
	v_cvt_pk_bf16_f32 v43, v44, v45
	global_store_dwordx2 v[90:91], v[42:43], off offset:3072
	v_pk_mul_f32 v[42:43], v[108:109], v[0:1] op_sel_hi:[1,0]
	v_pk_mul_f32 v[44:45], v[104:105], v[0:1] op_sel_hi:[1,0]
	v_pk_mul_f32 v[42:43], v[32:33], v[42:43]
	v_pk_mul_f32 v[44:45], v[30:31], v[44:45]
	v_pk_fma_f32 v[36:37], v[40:41], v[42:43], v[156:157]
	v_pk_fma_f32 v[34:35], v[38:39], v[44:45], v[154:155]
	s_nop 0
	v_cvt_pk_bf16_f32 v34, v34, v35
	v_cvt_pk_bf16_f32 v35, v36, v37
	global_store_dwordx2 v[90:91], v[34:35], off offset:3584
	s_cbranch_scc0 .Lnh2_exit
	s_cmpk_gt_i32 s4, 0x1fff
	s_cbranch_scc1 .LBB0_1600
	s_branch .Lnh2_B
.Lnh2_exit:
.LBB0_1601:
	s_waitcnt vmcnt(0)
	s_barrier
	v_mbcnt_lo_u32_b32 v0, -1, 0
	v_mbcnt_hi_u32_b32 v0, -1, v0
	s_nop 0
	v_sub_u32_e32 v0, 0, v0
	v_cmp_eq_u32_e32 vcc, s81, v0
	s_and_saveexec_b64 s[4:5], vcc
	s_cbranch_execz .LBB0_1645
	v_readlane_b32 s6, v252, 13
	v_readlane_b32 s8, v254, 9
	v_readlane_b32 s42, v252, 15
	v_readlane_b32 s7, v252, 14
	v_mov_b32_e32 v0, s8
	s_waitcnt vmcnt(0) expcnt(0) lgkmcnt(0)
	ds_read_b32 v2, v0
	v_readlane_b32 s8, v254, 10
	s_waitcnt lgkmcnt(0)
	v_cmp_ne_u32_e32 vcc, 0, v2
	v_mov_b32_e32 v0, s8
	ds_read_b32 v0, v0
	s_cbranch_vccnz .LBB0_1616
	v_readlane_b32 s8, v252, 10
	v_readlane_b32 s9, v252, 11
	s_load_dwordx2 s[12:13], s[8:9], 0x4
	s_add_u32 s8, s6, 0x1000
	s_addc_u32 s9, s7, 0
	s_add_u32 s10, s6, 0x1100
	s_addc_u32 s11, s7, 0
	s_waitcnt lgkmcnt(0)
	s_mul_i32 s36, s12, s3
	s_add_u32 s12, s6, 0x1200
	s_mul_i32 s36, s36, s13
	s_addc_u32 s13, s7, 0
	s_add_u32 s14, s6, 0x1300
	s_addc_u32 s15, s7, 0
	s_mov_b32 s37, 1
	s_mov_b64 s[16:17], 0
	s_branch .LBB0_1606
